# RWKV long-scan step loop hand-scheduled (16-step unrolled fast path, fused DPP adds, single-buffered LDS operand regs)
# speedup vs baseline: 1.0259x; 1.0259x over previous
; #define SCAN_INTERLEAVE(nds, nvalu)                                   \
;   _Pragma("unroll") for (int i_ = 0; i_ < (nds); ++i_) {               \
;     __builtin_amdgcn_sched_group_barrier(0x100, 1, 0);                 \
;     __builtin_amdgcn_sched_group_barrier(0x002, (nvalu), 0);           \
;   }
; __device__ __forceinline__ void scan_rwkv(const Params& p, int l, int seq, int h, char* smem, const unsigned* wflags, unsigned wexpect) {
;     ...
;     const int nsteps = min(16, T - c * 16);
;     const float* vb = vec + cur * 16 * 384;
;     const float* sb = scb + cur * 64;
;     RwRegs RA, RB;
;     float* ydummy = yb + 16 * 64 + tid * 2;
;     rw_load(RA, vb, sb, 0, k0, vrow0);
;     for (int t = 0; t < nsteps; t += 2) {
;       rw_load(RB, vb, sb, min(t + 1, 15), k0, vrow0);
;       const f32x2 y0v = rw_step(S, RA);
;       *(f32x2*)((part == 0) ? (yb + t * 64 + vrow0) : ydummy) = y0v;
;       SCAN_INTERLEAVE(13, 4);
;       if (t + 1 < nsteps) {
;         rw_load(RA, vb, sb, min(t + 2, 15), k0, vrow0);
;         const f32x2 y1v = rw_step(S, RB);
;         *(f32x2*)((part == 0) ? (yb + (t + 1) * 64 + vrow0) : ydummy) = y1v;
;         SCAN_INTERLEAVE(13, 4);
;       }
;     }
.LBB0_278:
	s_or_b64 exec, exec, s[38:39]
	s_lshl_b32 s27, s14, 4
	s_sub_i32 s39, s18, s27
	s_min_i32 s38, s39, 16
	s_cmp_lt_i32 s39, 1
	s_cbranch_scc1 .LBB0_283
	s_cmp_lg_u32 s38, 16
	s_cbranch_scc1 .Lrwf_slow0
	v_add_u32_e32 v141, 0xc200, v198
	v_mov_b32_e32 v138, v152
	v_mov_b32_e32 v139, v195
	v_mov_b32_e32 v140, 0
	v_cndmask_b32_e64 v141, v194, v141, s[44:45]
	s_mov_b32 s39, 0
	s_branch .Lrwf_body
.Lrwf_slow0:
	ds_read_b128 v[68:71], v3 offset:49152
	ds_read_b64 v[26:27], v195 offset:1280
	s_waitcnt lgkmcnt(1)
	ds_read_b128 v[70:73], v152
	ds_read_b128 v[74:77], v152 offset:16
	ds_read_b128 v[106:109], v152 offset:1040
	ds_read_b128 v[90:93], v152 offset:1024
	ds_read_b128 v[102:105], v152 offset:784
	ds_read_b128 v[86:89], v152 offset:768
	ds_read_b128 v[98:101], v152 offset:272
	ds_read_b128 v[82:85], v152 offset:256
	ds_read_b128 v[94:97], v152 offset:528
	ds_read_b128 v[78:81], v152 offset:512
	s_mov_b32 s39, 0
	s_mov_b32 s46, 0xc010
	v_mov_b32_e32 v205, v200
	v_mov_b32_e32 v206, v199
	v_mov_b32_e32 v207, v198
	s_branch .LBB0_281

; #define SCAN_INTERLEAVE(nds, nvalu)                                   \
;   _Pragma("unroll") for (int i_ = 0; i_ < (nds); ++i_) {               \
;     __builtin_amdgcn_sched_group_barrier(0x100, 1, 0);                 \
;     __builtin_amdgcn_sched_group_barrier(0x002, (nvalu), 0);           \
;   }
; __device__ __forceinline__ void scan_rwkv(const Params& p, int l, int seq, int h, char* smem, const unsigned* wflags, unsigned wexpect) {
;     ...
;     const int nsteps = min(16, T - c * 16);
;     const float* vb = vec + cur * 16 * 384;
;     const float* sb = scb + cur * 64;
;     RwRegs RA, RB;
;     float* ydummy = yb + 16 * 64 + tid * 2;
;     rw_load(RA, vb, sb, 0, k0, vrow0);
;     for (int t = 0; t < nsteps; t += 2) {
;       rw_load(RB, vb, sb, min(t + 1, 15), k0, vrow0);
;       const f32x2 y0v = rw_step(S, RA);
;       *(f32x2*)((part == 0) ? (yb + t * 64 + vrow0) : ydummy) = y0v;
;       SCAN_INTERLEAVE(13, 4);
;       if (t + 1 < nsteps) {
;         rw_load(RA, vb, sb, min(t + 2, 15), k0, vrow0);
;         const f32x2 y1v = rw_step(S, RB);
;         *(f32x2*)((part == 0) ? (yb + (t + 1) * 64 + vrow0) : ydummy) = y1v;
;         SCAN_INTERLEAVE(13, 4);
;       }
;     }
.LBB0_296:
	s_or_b64 exec, exec, s[38:39]
	s_lshl_b32 s14, s27, 4
	s_sub_i32 s38, s18, s14
	s_min_i32 s27, s38, 16
	s_cmp_lt_i32 s38, 1
	s_cbranch_scc1 .LBB0_301
	s_cmp_lg_u32 s27, 16
	s_cbranch_scc1 .Lrwf_slow1
	v_add_u32_e32 v141, 0xc200, v198
	v_add_u32_e32 v138, 0x6000, v152
	v_add_u32_e32 v139, 0x6000, v195
	v_mov_b32_e32 v140, 0x100
	v_cndmask_b32_e64 v141, v194, v141, s[44:45]
	s_mov_b32 s39, 1
	s_branch .Lrwf_body
.Lrwf_slow1:
	ds_read_b128 v[68:71], v3 offset:49408
	ds_read_b64 v[26:27], v195 offset:25856
	s_waitcnt lgkmcnt(1)
	ds_read_b128 v[70:73], v152 offset:24576
	ds_read_b128 v[74:77], v152 offset:24592
	ds_read_b128 v[106:109], v152 offset:25616
	ds_read_b128 v[90:93], v152 offset:25600
	ds_read_b128 v[102:105], v152 offset:25360
	ds_read_b128 v[86:89], v152 offset:25344
	ds_read_b128 v[98:101], v152 offset:24848
	ds_read_b128 v[82:85], v152 offset:24832
	ds_read_b128 v[94:97], v152 offset:25104
	ds_read_b128 v[78:81], v152 offset:25088
	s_mov_b32 s38, 0
	s_mov_b32 s39, 0xc110
	v_mov_b32_e32 v205, v202
	v_mov_b32_e32 v206, v201
	v_mov_b32_e32 v207, v198
	s_branch .LBB0_299

; __device__ __forceinline__ void rw_load(RwRegs& R, const float* vb, const float* sb, int t, int k0, int vrow0) {
;   const float* vt = vb + t * 384 + k0;
; #pragma unroll
;   for (int q = 0; q < 2; ++q) {
;     R.a[q] = *(const f32x4*)(vt + q * 4);
;     R.wr[q] = *(const f32x4*)(vt + 128 + q * 4);
;     R.w[q] = *(const f32x4*)(vt + 64 + q * 4);
;     R.b[q] = *(const f32x4*)(vt + 192 + q * 4);
;     R.k[q] = *(const f32x4*)(vt + 256 + q * 4);
;   }
;   R.v = *(const f32x2*)(vb + t * 384 + 320 + vrow0);
;   R.sc = *(const f32x4*)(sb + t * 4);
; }
; __device__ __forceinline__ f32x2 rw_step(f32x2 (&S)[2][4], const RwRegs& R) {
;   float sa[2], sy[2];
; #pragma unroll
;   for (int r = 0; r < 2; ++r) {
;     f32x2 a0 = S[r][0] * lo2(R.a[0]);
;     f32x2 a1 = S[r][1] * hi2(R.a[0]);
;     f32x2 y0 = S[r][0] * lo2(R.wr[0]);
;     f32x2 y1 = S[r][1] * hi2(R.wr[0]);
;     a0 += S[r][2] * lo2(R.a[1]);
;     a1 += S[r][3] * hi2(R.a[1]);
;     y0 += S[r][2] * lo2(R.wr[1]);
;     y1 += S[r][3] * hi2(R.wr[1]);
;     a0 += a1; y0 += y1;
;     sa[r] = a0.x + a0.y; sy[r] = y0.x + y0.y;
;   }
;   sa[0] = red8(sa[0]); sa[1] = red8(sa[1]); sy[0] = red8(sy[0]); sy[1] = red8(sy[1]);
;   f32x2 yv;
; #pragma unroll
;   for (int r = 0; r < 2; ++r) {
;     const float vr = r ? R.v.y : R.v.x;
;     const f32x2 sa2 = splat2(sa[r]), vv2 = splat2(vr);
;     S[r][0] = S[r][0] * lo2(R.w[0]) + (sa2 * lo2(R.b[0]) + vv2 * lo2(R.k[0]));
;     S[r][1] = S[r][1] * hi2(R.w[0]) + (sa2 * hi2(R.b[0]) + vv2 * hi2(R.k[0]));
;     S[r][2] = S[r][2] * lo2(R.w[1]) + (sa2 * lo2(R.b[1]) + vv2 * lo2(R.k[1]));
;     S[r][3] = S[r][3] * hi2(R.w[1]) + (sa2 * hi2(R.b[1]) + vv2 * hi2(R.k[1]));
;     const float y = sy[r] + sa[r] * R.sc.x + vr * R.sc.y;
;     if (r) yv.y = y; else yv.x = y;
;   }
;   return yv;
; }
; __device__ __forceinline__ void scan_rwkv(const Params& p, int l, int seq, int h, char* smem, const unsigned* wflags, unsigned wexpect) {
;     ...
;     for (int t = 0; t < nsteps; t += 2) {
;       rw_load(RB, vb, sb, min(t + 1, 15), k0, vrow0);
;       const f32x2 y0v = rw_step(S, RA);
;       *(f32x2*)((part == 0) ? (yb + t * 64 + vrow0) : ydummy) = y0v;
;       SCAN_INTERLEAVE(13, 4);
;       if (t + 1 < nsteps) {
;         rw_load(RA, vb, sb, min(t + 2, 15), k0, vrow0);
;         const f32x2 y1v = rw_step(S, RB);
;         *(f32x2*)((part == 0) ? (yb + (t + 1) * 64 + vrow0) : ydummy) = y1v;
.Lrwf_body:
	ds_read_b128 v[68:71], v138 offset:0
	ds_read_b128 v[72:75], v138 offset:16
	ds_read_b128 v[76:79], v138 offset:512
	ds_read_b128 v[80:83], v138 offset:528
	ds_read_b128 v[100:103], v138 offset:1024
	ds_read_b128 v[104:107], v138 offset:1040
	ds_read_b64 v[108:109], v139 offset:1280
	ds_read_b64 v[110:111], v140 offset:49152
	ds_read_b128 v[92:95], v138 offset:768
	ds_read_b128 v[96:99], v138 offset:784
	ds_read_b128 v[84:87], v138 offset:256
	ds_read_b128 v[88:91], v138 offset:272
	s_waitcnt lgkmcnt(8)
	v_pk_mul_f32 v[128:129], v[8:9], v[68:69]
	v_pk_mul_f32 v[132:133], v[8:9], v[76:77]
	v_pk_mul_f32 v[130:131], v[16:17], v[68:69]
	v_pk_mul_f32 v[134:135], v[16:17], v[76:77]
	v_pk_fma_f32 v[128:129], v[10:11], v[70:71], v[128:129]
	v_pk_fma_f32 v[132:133], v[10:11], v[78:79], v[132:133]
	v_pk_fma_f32 v[130:131], v[18:19], v[70:71], v[130:131]
	v_pk_fma_f32 v[134:135], v[18:19], v[78:79], v[134:135]
	v_pk_fma_f32 v[128:129], v[4:5], v[72:73], v[128:129]
	v_pk_fma_f32 v[132:133], v[4:5], v[80:81], v[132:133]
	v_pk_fma_f32 v[130:131], v[12:13], v[72:73], v[130:131]
	v_pk_fma_f32 v[134:135], v[12:13], v[80:81], v[134:135]
	v_pk_fma_f32 v[128:129], v[6:7], v[74:75], v[128:129]
	v_pk_fma_f32 v[132:133], v[6:7], v[82:83], v[132:133]
	v_pk_fma_f32 v[130:131], v[14:15], v[74:75], v[130:131]
	v_pk_fma_f32 v[134:135], v[14:15], v[82:83], v[134:135]
	ds_read_b128 v[68:71], v138 offset:1536
	ds_read_b128 v[72:75], v138 offset:1552
	ds_read_b128 v[76:79], v138 offset:2048
	ds_read_b128 v[80:83], v138 offset:2064
	s_waitcnt lgkmcnt(9)
	v_pk_mul_f32 v[112:113], v[108:109], v[100:101] op_sel_hi:[0,1]
	v_pk_mul_f32 v[120:121], v[108:109], v[100:101] op_sel:[1,0]
	v_add_f32_e32 v128, v128, v129
	v_add_f32_e32 v132, v132, v133
	v_add_f32_e32 v129, v130, v131
	v_add_f32_e32 v133, v134, v135
	v_pk_mul_f32 v[114:115], v[108:109], v[102:103] op_sel_hi:[0,1]
	v_pk_mul_f32 v[122:123], v[108:109], v[102:103] op_sel:[1,0]
	v_add_f32_dpp v128, v128, v128 quad_perm:[1,0,3,2] row_mask:0xf bank_mask:0xf bound_ctrl:1
	v_add_f32_dpp v132, v132, v132 quad_perm:[1,0,3,2] row_mask:0xf bank_mask:0xf bound_ctrl:1
	v_add_f32_dpp v129, v129, v129 quad_perm:[1,0,3,2] row_mask:0xf bank_mask:0xf bound_ctrl:1
	v_add_f32_dpp v133, v133, v133 quad_perm:[1,0,3,2] row_mask:0xf bank_mask:0xf bound_ctrl:1
	v_pk_mul_f32 v[116:117], v[108:109], v[104:105] op_sel_hi:[0,1]
	v_pk_mul_f32 v[124:125], v[108:109], v[104:105] op_sel:[1,0]
	v_add_f32_dpp v128, v128, v128 quad_perm:[2,3,0,1] row_mask:0xf bank_mask:0xf bound_ctrl:1
	v_add_f32_dpp v132, v132, v132 quad_perm:[2,3,0,1] row_mask:0xf bank_mask:0xf bound_ctrl:1
	v_add_f32_dpp v129, v129, v129 quad_perm:[2,3,0,1] row_mask:0xf bank_mask:0xf bound_ctrl:1
	v_add_f32_dpp v133, v133, v133 quad_perm:[2,3,0,1] row_mask:0xf bank_mask:0xf bound_ctrl:1
	v_pk_mul_f32 v[118:119], v[108:109], v[106:107] op_sel_hi:[0,1]
	v_pk_mul_f32 v[126:127], v[108:109], v[106:107] op_sel:[1,0]
	v_add_f32_dpp v128, v128, v128 row_half_mirror row_mask:0xf bank_mask:0xf bound_ctrl:1
	v_add_f32_dpp v132, v132, v132 row_half_mirror row_mask:0xf bank_mask:0xf bound_ctrl:1
	v_add_f32_dpp v129, v129, v129 row_half_mirror row_mask:0xf bank_mask:0xf bound_ctrl:1
	v_add_f32_dpp v133, v133, v133 row_half_mirror row_mask:0xf bank_mask:0xf bound_ctrl:1
	ds_read_b128 v[100:103], v138 offset:2560
	ds_read_b128 v[104:107], v138 offset:2576
	s_waitcnt lgkmcnt(10)
	v_pk_fma_f32 v[136:137], v[128:129], v[110:111], v[132:133] op_sel_hi:[1,0,1]
	s_waitcnt lgkmcnt(8)
	v_pk_fma_f32 v[112:113], v[92:93], v[128:129], v[112:113] op_sel_hi:[1,0,1]
	v_pk_fma_f32 v[136:137], v[108:109], v[110:111], v[136:137] op_sel:[0,1,0]
	v_pk_fma_f32 v[120:121], v[92:93], v[128:129], v[120:121] op_sel:[0,1,0]
	ds_read_b64 v[108:109], v139 offset:2816
	ds_read_b64 v[110:111], v140 offset:49168
	s_waitcnt lgkmcnt(8)
	v_pk_fma_f32 v[8:9], v[8:9], v[84:85], v[112:113]
	ds_write_b64 v141, v[136:137] offset:0
	v_pk_fma_f32 v[16:17], v[16:17], v[84:85], v[120:121]
	v_pk_fma_f32 v[114:115], v[94:95], v[128:129], v[114:115] op_sel_hi:[1,0,1]
	v_pk_fma_f32 v[122:123], v[94:95], v[128:129], v[122:123] op_sel:[0,1,0]
	v_pk_fma_f32 v[10:11], v[10:11], v[86:87], v[114:115]
	v_pk_fma_f32 v[18:19], v[18:19], v[86:87], v[122:123]
	v_pk_fma_f32 v[116:117], v[96:97], v[128:129], v[116:117] op_sel_hi:[1,0,1]
	v_pk_fma_f32 v[124:125], v[96:97], v[128:129], v[124:125] op_sel:[0,1,0]
	v_pk_fma_f32 v[4:5], v[4:5], v[88:89], v[116:117]
	v_pk_fma_f32 v[12:13], v[12:13], v[88:89], v[124:125]
	v_pk_fma_f32 v[118:119], v[98:99], v[128:129], v[118:119] op_sel_hi:[1,0,1]
	v_pk_fma_f32 v[126:127], v[98:99], v[128:129], v[126:127] op_sel:[0,1,0]
	v_pk_fma_f32 v[6:7], v[6:7], v[90:91], v[118:119]
	v_pk_fma_f32 v[14:15], v[14:15], v[90:91], v[126:127]
	ds_read_b128 v[92:95], v138 offset:2304
	ds_read_b128 v[96:99], v138 offset:2320
	ds_read_b128 v[84:87], v138 offset:1792
	ds_read_b128 v[88:91], v138 offset:1808
	s_waitcnt lgkmcnt(9)
	v_pk_mul_f32 v[128:129], v[8:9], v[68:69]
	v_pk_mul_f32 v[132:133], v[8:9], v[76:77]
	v_pk_mul_f32 v[130:131], v[16:17], v[68:69]
	v_pk_mul_f32 v[134:135], v[16:17], v[76:77]
	v_pk_fma_f32 v[128:129], v[10:11], v[70:71], v[128:129]
	v_pk_fma_f32 v[132:133], v[10:11], v[78:79], v[132:133]
	v_pk_fma_f32 v[130:131], v[18:19], v[70:71], v[130:131]
	v_pk_fma_f32 v[134:135], v[18:19], v[78:79], v[134:135]
	v_pk_fma_f32 v[128:129], v[4:5], v[72:73], v[128:129]
	v_pk_fma_f32 v[132:133], v[4:5], v[80:81], v[132:133]
	v_pk_fma_f32 v[130:131], v[12:13], v[72:73], v[130:131]
	v_pk_fma_f32 v[134:135], v[12:13], v[80:81], v[134:135]
	v_pk_fma_f32 v[128:129], v[6:7], v[74:75], v[128:129]
	v_pk_fma_f32 v[132:133], v[6:7], v[82:83], v[132:133]
	v_pk_fma_f32 v[130:131], v[14:15], v[74:75], v[130:131]
	v_pk_fma_f32 v[134:135], v[14:15], v[82:83], v[134:135]
	ds_read_b128 v[68:71], v138 offset:3072
	ds_read_b128 v[72:75], v138 offset:3088
	ds_read_b128 v[76:79], v138 offset:3584
	ds_read_b128 v[80:83], v138 offset:3600
	s_waitcnt lgkmcnt(10)
; __device__ __forceinline__ void rw_load(RwRegs& R, const float* vb, const float* sb, int t, int k0, int vrow0) {
;   const float* vt = vb + t * 384 + k0;
; #pragma unroll
;   for (int q = 0; q < 2; ++q) {
;     R.a[q] = *(const f32x4*)(vt + q * 4);
;     R.wr[q] = *(const f32x4*)(vt + 128 + q * 4);
;     R.w[q] = *(const f32x4*)(vt + 64 + q * 4);
;     R.b[q] = *(const f32x4*)(vt + 192 + q * 4);
;     R.k[q] = *(const f32x4*)(vt + 256 + q * 4);
;   }
;   R.v = *(const f32x2*)(vb + t * 384 + 320 + vrow0);
;   R.sc = *(const f32x4*)(sb + t * 4);
; }
; __device__ __forceinline__ f32x2 rw_step(f32x2 (&S)[2][4], const RwRegs& R) {
;   float sa[2], sy[2];
; #pragma unroll
;   for (int r = 0; r < 2; ++r) {
;     f32x2 a0 = S[r][0] * lo2(R.a[0]);
;     f32x2 a1 = S[r][1] * hi2(R.a[0]);
;     f32x2 y0 = S[r][0] * lo2(R.wr[0]);
;     f32x2 y1 = S[r][1] * hi2(R.wr[0]);
;     a0 += S[r][2] * lo2(R.a[1]);
;     a1 += S[r][3] * hi2(R.a[1]);
;     y0 += S[r][2] * lo2(R.wr[1]);
;     y1 += S[r][3] * hi2(R.wr[1]);
;     a0 += a1; y0 += y1;
;     sa[r] = a0.x + a0.y; sy[r] = y0.x + y0.y;
;   }
;   sa[0] = red8(sa[0]); sa[1] = red8(sa[1]); sy[0] = red8(sy[0]); sy[1] = red8(sy[1]);
;   f32x2 yv;
; #pragma unroll
;   for (int r = 0; r < 2; ++r) {
;     const float vr = r ? R.v.y : R.v.x;
;     const f32x2 sa2 = splat2(sa[r]), vv2 = splat2(vr);
;     S[r][0] = S[r][0] * lo2(R.w[0]) + (sa2 * lo2(R.b[0]) + vv2 * lo2(R.k[0]));
;     S[r][1] = S[r][1] * hi2(R.w[0]) + (sa2 * hi2(R.b[0]) + vv2 * hi2(R.k[0]));
;     S[r][2] = S[r][2] * lo2(R.w[1]) + (sa2 * lo2(R.b[1]) + vv2 * lo2(R.k[1]));
;     S[r][3] = S[r][3] * hi2(R.w[1]) + (sa2 * hi2(R.b[1]) + vv2 * hi2(R.k[1]));
;     const float y = sy[r] + sa[r] * R.sc.x + vr * R.sc.y;
;     if (r) yv.y = y; else yv.x = y;
;   }
;   return yv;
; }
; __device__ __forceinline__ void scan_rwkv(const Params& p, int l, int seq, int h, char* smem, const unsigned* wflags, unsigned wexpect) {
;     ...
;     for (int t = 0; t < nsteps; t += 2) {
;       rw_load(RB, vb, sb, min(t + 1, 15), k0, vrow0);
;       const f32x2 y0v = rw_step(S, RA);
;       *(f32x2*)((part == 0) ? (yb + t * 64 + vrow0) : ydummy) = y0v;
;       SCAN_INTERLEAVE(13, 4);
;       if (t + 1 < nsteps) {
;         rw_load(RA, vb, sb, min(t + 2, 15), k0, vrow0);
;         const f32x2 y1v = rw_step(S, RB);
;         *(f32x2*)((part == 0) ? (yb + (t + 1) * 64 + vrow0) : ydummy) = y1v;
	v_pk_mul_f32 v[112:113], v[108:109], v[100:101] op_sel_hi:[0,1]
	v_pk_mul_f32 v[120:121], v[108:109], v[100:101] op_sel:[1,0]
	v_add_f32_e32 v128, v128, v129
	v_add_f32_e32 v132, v132, v133
	v_add_f32_e32 v129, v130, v131
	v_add_f32_e32 v133, v134, v135
	v_pk_mul_f32 v[114:115], v[108:109], v[102:103] op_sel_hi:[0,1]
	v_pk_mul_f32 v[122:123], v[108:109], v[102:103] op_sel:[1,0]
	v_add_f32_dpp v128, v128, v128 quad_perm:[1,0,3,2] row_mask:0xf bank_mask:0xf bound_ctrl:1
	v_add_f32_dpp v132, v132, v132 quad_perm:[1,0,3,2] row_mask:0xf bank_mask:0xf bound_ctrl:1
	v_add_f32_dpp v129, v129, v129 quad_perm:[1,0,3,2] row_mask:0xf bank_mask:0xf bound_ctrl:1
	v_add_f32_dpp v133, v133, v133 quad_perm:[1,0,3,2] row_mask:0xf bank_mask:0xf bound_ctrl:1
	v_pk_mul_f32 v[116:117], v[108:109], v[104:105] op_sel_hi:[0,1]
	v_pk_mul_f32 v[124:125], v[108:109], v[104:105] op_sel:[1,0]
	v_add_f32_dpp v128, v128, v128 quad_perm:[2,3,0,1] row_mask:0xf bank_mask:0xf bound_ctrl:1
	v_add_f32_dpp v132, v132, v132 quad_perm:[2,3,0,1] row_mask:0xf bank_mask:0xf bound_ctrl:1
	v_add_f32_dpp v129, v129, v129 quad_perm:[2,3,0,1] row_mask:0xf bank_mask:0xf bound_ctrl:1
	v_add_f32_dpp v133, v133, v133 quad_perm:[2,3,0,1] row_mask:0xf bank_mask:0xf bound_ctrl:1
	v_pk_mul_f32 v[118:119], v[108:109], v[106:107] op_sel_hi:[0,1]
	v_pk_mul_f32 v[126:127], v[108:109], v[106:107] op_sel:[1,0]
	v_add_f32_dpp v128, v128, v128 row_half_mirror row_mask:0xf bank_mask:0xf bound_ctrl:1
	v_add_f32_dpp v132, v132, v132 row_half_mirror row_mask:0xf bank_mask:0xf bound_ctrl:1
	v_add_f32_dpp v129, v129, v129 row_half_mirror row_mask:0xf bank_mask:0xf bound_ctrl:1
	v_add_f32_dpp v133, v133, v133 row_half_mirror row_mask:0xf bank_mask:0xf bound_ctrl:1
	ds_read_b128 v[100:103], v138 offset:4096
	ds_read_b128 v[104:107], v138 offset:4112
	s_waitcnt lgkmcnt(11)
	v_pk_fma_f32 v[136:137], v[128:129], v[110:111], v[132:133] op_sel_hi:[1,0,1]
	s_waitcnt lgkmcnt(8)
	v_pk_fma_f32 v[112:113], v[92:93], v[128:129], v[112:113] op_sel_hi:[1,0,1]
	v_pk_fma_f32 v[136:137], v[108:109], v[110:111], v[136:137] op_sel:[0,1,0]
	v_pk_fma_f32 v[120:121], v[92:93], v[128:129], v[120:121] op_sel:[0,1,0]
	ds_read_b64 v[108:109], v139 offset:4352
	ds_read_b64 v[110:111], v140 offset:49184
	s_waitcnt lgkmcnt(8)
	v_pk_fma_f32 v[8:9], v[8:9], v[84:85], v[112:113]
	ds_write_b64 v141, v[136:137] offset:256
	v_pk_fma_f32 v[16:17], v[16:17], v[84:85], v[120:121]
	v_pk_fma_f32 v[114:115], v[94:95], v[128:129], v[114:115] op_sel_hi:[1,0,1]
	v_pk_fma_f32 v[122:123], v[94:95], v[128:129], v[122:123] op_sel:[0,1,0]
	v_pk_fma_f32 v[10:11], v[10:11], v[86:87], v[114:115]
	v_pk_fma_f32 v[18:19], v[18:19], v[86:87], v[122:123]
	v_pk_fma_f32 v[116:117], v[96:97], v[128:129], v[116:117] op_sel_hi:[1,0,1]
	v_pk_fma_f32 v[124:125], v[96:97], v[128:129], v[124:125] op_sel:[0,1,0]
	v_pk_fma_f32 v[4:5], v[4:5], v[88:89], v[116:117]
	v_pk_fma_f32 v[12:13], v[12:13], v[88:89], v[124:125]
	v_pk_fma_f32 v[118:119], v[98:99], v[128:129], v[118:119] op_sel_hi:[1,0,1]
	v_pk_fma_f32 v[126:127], v[98:99], v[128:129], v[126:127] op_sel:[0,1,0]
	v_pk_fma_f32 v[6:7], v[6:7], v[90:91], v[118:119]
	v_pk_fma_f32 v[14:15], v[14:15], v[90:91], v[126:127]
	ds_read_b128 v[92:95], v138 offset:3840
	ds_read_b128 v[96:99], v138 offset:3856
	ds_read_b128 v[84:87], v138 offset:3328
	ds_read_b128 v[88:91], v138 offset:3344
	s_waitcnt lgkmcnt(9)
	v_pk_mul_f32 v[128:129], v[8:9], v[68:69]
	v_pk_mul_f32 v[132:133], v[8:9], v[76:77]
	v_pk_mul_f32 v[130:131], v[16:17], v[68:69]
	v_pk_mul_f32 v[134:135], v[16:17], v[76:77]
	v_pk_fma_f32 v[128:129], v[10:11], v[70:71], v[128:129]
	v_pk_fma_f32 v[132:133], v[10:11], v[78:79], v[132:133]
	v_pk_fma_f32 v[130:131], v[18:19], v[70:71], v[130:131]
	v_pk_fma_f32 v[134:135], v[18:19], v[78:79], v[134:135]
	v_pk_fma_f32 v[128:129], v[4:5], v[72:73], v[128:129]
	v_pk_fma_f32 v[132:133], v[4:5], v[80:81], v[132:133]
	v_pk_fma_f32 v[130:131], v[12:13], v[72:73], v[130:131]
	v_pk_fma_f32 v[134:135], v[12:13], v[80:81], v[134:135]
	v_pk_fma_f32 v[128:129], v[6:7], v[74:75], v[128:129]
	v_pk_fma_f32 v[132:133], v[6:7], v[82:83], v[132:133]
	v_pk_fma_f32 v[130:131], v[14:15], v[74:75], v[130:131]
	v_pk_fma_f32 v[134:135], v[14:15], v[82:83], v[134:135]
	ds_read_b128 v[68:71], v138 offset:4608
	ds_read_b128 v[72:75], v138 offset:4624
	ds_read_b128 v[76:79], v138 offset:5120
	ds_read_b128 v[80:83], v138 offset:5136
	s_waitcnt lgkmcnt(10)
	v_pk_mul_f32 v[112:113], v[108:109], v[100:101] op_sel_hi:[0,1]
	v_pk_mul_f32 v[120:121], v[108:109], v[100:101] op_sel:[1,0]
	v_add_f32_e32 v128, v128, v129
	v_add_f32_e32 v132, v132, v133
	v_add_f32_e32 v129, v130, v131
	v_add_f32_e32 v133, v134, v135
	v_pk_mul_f32 v[114:115], v[108:109], v[102:103] op_sel_hi:[0,1]
	v_pk_mul_f32 v[122:123], v[108:109], v[102:103] op_sel:[1,0]
	v_add_f32_dpp v128, v128, v128 quad_perm:[1,0,3,2] row_mask:0xf bank_mask:0xf bound_ctrl:1
	v_add_f32_dpp v132, v132, v132 quad_perm:[1,0,3,2] row_mask:0xf bank_mask:0xf bound_ctrl:1
	v_add_f32_dpp v129, v129, v129 quad_perm:[1,0,3,2] row_mask:0xf bank_mask:0xf bound_ctrl:1
	v_add_f32_dpp v133, v133, v133 quad_perm:[1,0,3,2] row_mask:0xf bank_mask:0xf bound_ctrl:1
	v_pk_mul_f32 v[116:117], v[108:109], v[104:105] op_sel_hi:[0,1]
	v_pk_mul_f32 v[124:125], v[108:109], v[104:105] op_sel:[1,0]
	v_add_f32_dpp v128, v128, v128 quad_perm:[2,3,0,1] row_mask:0xf bank_mask:0xf bound_ctrl:1
	v_add_f32_dpp v132, v132, v132 quad_perm:[2,3,0,1] row_mask:0xf bank_mask:0xf bound_ctrl:1
	v_add_f32_dpp v129, v129, v129 quad_perm:[2,3,0,1] row_mask:0xf bank_mask:0xf bound_ctrl:1
	v_add_f32_dpp v133, v133, v133 quad_perm:[2,3,0,1] row_mask:0xf bank_mask:0xf bound_ctrl:1
	v_pk_mul_f32 v[118:119], v[108:109], v[106:107] op_sel_hi:[0,1]
	v_pk_mul_f32 v[126:127], v[108:109], v[106:107] op_sel:[1,0]
	v_add_f32_dpp v128, v128, v128 row_half_mirror row_mask:0xf bank_mask:0xf bound_ctrl:1
	v_add_f32_dpp v132, v132, v132 row_half_mirror row_mask:0xf bank_mask:0xf bound_ctrl:1
	v_add_f32_dpp v129, v129, v129 row_half_mirror row_mask:0xf bank_mask:0xf bound_ctrl:1
	v_add_f32_dpp v133, v133, v133 row_half_mirror row_mask:0xf bank_mask:0xf bound_ctrl:1
	ds_read_b128 v[100:103], v138 offset:5632
	ds_read_b128 v[104:107], v138 offset:5648
	s_waitcnt lgkmcnt(11)
; __device__ __forceinline__ void rw_load(RwRegs& R, const float* vb, const float* sb, int t, int k0, int vrow0) {
;   const float* vt = vb + t * 384 + k0;
; #pragma unroll
;   for (int q = 0; q < 2; ++q) {
;     R.a[q] = *(const f32x4*)(vt + q * 4);
;     R.wr[q] = *(const f32x4*)(vt + 128 + q * 4);
;     R.w[q] = *(const f32x4*)(vt + 64 + q * 4);
;     R.b[q] = *(const f32x4*)(vt + 192 + q * 4);
;     R.k[q] = *(const f32x4*)(vt + 256 + q * 4);
;   }
;   R.v = *(const f32x2*)(vb + t * 384 + 320 + vrow0);
;   R.sc = *(const f32x4*)(sb + t * 4);
; }
; __device__ __forceinline__ f32x2 rw_step(f32x2 (&S)[2][4], const RwRegs& R) {
;   float sa[2], sy[2];
; #pragma unroll
;   for (int r = 0; r < 2; ++r) {
;     f32x2 a0 = S[r][0] * lo2(R.a[0]);
;     f32x2 a1 = S[r][1] * hi2(R.a[0]);
;     f32x2 y0 = S[r][0] * lo2(R.wr[0]);
;     f32x2 y1 = S[r][1] * hi2(R.wr[0]);
;     a0 += S[r][2] * lo2(R.a[1]);
;     a1 += S[r][3] * hi2(R.a[1]);
;     y0 += S[r][2] * lo2(R.wr[1]);
;     y1 += S[r][3] * hi2(R.wr[1]);
;     a0 += a1; y0 += y1;
;     sa[r] = a0.x + a0.y; sy[r] = y0.x + y0.y;
;   }
;   sa[0] = red8(sa[0]); sa[1] = red8(sa[1]); sy[0] = red8(sy[0]); sy[1] = red8(sy[1]);
;   f32x2 yv;
; #pragma unroll
;   for (int r = 0; r < 2; ++r) {
;     const float vr = r ? R.v.y : R.v.x;
;     const f32x2 sa2 = splat2(sa[r]), vv2 = splat2(vr);
;     S[r][0] = S[r][0] * lo2(R.w[0]) + (sa2 * lo2(R.b[0]) + vv2 * lo2(R.k[0]));
;     S[r][1] = S[r][1] * hi2(R.w[0]) + (sa2 * hi2(R.b[0]) + vv2 * hi2(R.k[0]));
;     S[r][2] = S[r][2] * lo2(R.w[1]) + (sa2 * lo2(R.b[1]) + vv2 * lo2(R.k[1]));
;     S[r][3] = S[r][3] * hi2(R.w[1]) + (sa2 * hi2(R.b[1]) + vv2 * hi2(R.k[1]));
;     const float y = sy[r] + sa[r] * R.sc.x + vr * R.sc.y;
;     if (r) yv.y = y; else yv.x = y;
;   }
;   return yv;
; }
; __device__ __forceinline__ void scan_rwkv(const Params& p, int l, int seq, int h, char* smem, const unsigned* wflags, unsigned wexpect) {
;     ...
;     for (int t = 0; t < nsteps; t += 2) {
;       rw_load(RB, vb, sb, min(t + 1, 15), k0, vrow0);
;       const f32x2 y0v = rw_step(S, RA);
;       *(f32x2*)((part == 0) ? (yb + t * 64 + vrow0) : ydummy) = y0v;
;       SCAN_INTERLEAVE(13, 4);
;       if (t + 1 < nsteps) {
;         rw_load(RA, vb, sb, min(t + 2, 15), k0, vrow0);
;         const f32x2 y1v = rw_step(S, RB);
;         *(f32x2*)((part == 0) ? (yb + (t + 1) * 64 + vrow0) : ydummy) = y1v;
	v_pk_fma_f32 v[136:137], v[128:129], v[110:111], v[132:133] op_sel_hi:[1,0,1]
	s_waitcnt lgkmcnt(8)
	v_pk_fma_f32 v[112:113], v[92:93], v[128:129], v[112:113] op_sel_hi:[1,0,1]
	v_pk_fma_f32 v[136:137], v[108:109], v[110:111], v[136:137] op_sel:[0,1,0]
	v_pk_fma_f32 v[120:121], v[92:93], v[128:129], v[120:121] op_sel:[0,1,0]
	ds_read_b64 v[108:109], v139 offset:5888
	ds_read_b64 v[110:111], v140 offset:49200
	s_waitcnt lgkmcnt(8)
	v_pk_fma_f32 v[8:9], v[8:9], v[84:85], v[112:113]
	ds_write_b64 v141, v[136:137] offset:512
	v_pk_fma_f32 v[16:17], v[16:17], v[84:85], v[120:121]
	v_pk_fma_f32 v[114:115], v[94:95], v[128:129], v[114:115] op_sel_hi:[1,0,1]
	v_pk_fma_f32 v[122:123], v[94:95], v[128:129], v[122:123] op_sel:[0,1,0]
	v_pk_fma_f32 v[10:11], v[10:11], v[86:87], v[114:115]
	v_pk_fma_f32 v[18:19], v[18:19], v[86:87], v[122:123]
	v_pk_fma_f32 v[116:117], v[96:97], v[128:129], v[116:117] op_sel_hi:[1,0,1]
	v_pk_fma_f32 v[124:125], v[96:97], v[128:129], v[124:125] op_sel:[0,1,0]
	v_pk_fma_f32 v[4:5], v[4:5], v[88:89], v[116:117]
	v_pk_fma_f32 v[12:13], v[12:13], v[88:89], v[124:125]
	v_pk_fma_f32 v[118:119], v[98:99], v[128:129], v[118:119] op_sel_hi:[1,0,1]
	v_pk_fma_f32 v[126:127], v[98:99], v[128:129], v[126:127] op_sel:[0,1,0]
	v_pk_fma_f32 v[6:7], v[6:7], v[90:91], v[118:119]
	v_pk_fma_f32 v[14:15], v[14:15], v[90:91], v[126:127]
	ds_read_b128 v[92:95], v138 offset:5376
	ds_read_b128 v[96:99], v138 offset:5392
	ds_read_b128 v[84:87], v138 offset:4864
	ds_read_b128 v[88:91], v138 offset:4880
	s_waitcnt lgkmcnt(9)
	v_pk_mul_f32 v[128:129], v[8:9], v[68:69]
	v_pk_mul_f32 v[132:133], v[8:9], v[76:77]
	v_pk_mul_f32 v[130:131], v[16:17], v[68:69]
	v_pk_mul_f32 v[134:135], v[16:17], v[76:77]
	v_pk_fma_f32 v[128:129], v[10:11], v[70:71], v[128:129]
	v_pk_fma_f32 v[132:133], v[10:11], v[78:79], v[132:133]
	v_pk_fma_f32 v[130:131], v[18:19], v[70:71], v[130:131]
	v_pk_fma_f32 v[134:135], v[18:19], v[78:79], v[134:135]
	v_pk_fma_f32 v[128:129], v[4:5], v[72:73], v[128:129]
	v_pk_fma_f32 v[132:133], v[4:5], v[80:81], v[132:133]
	v_pk_fma_f32 v[130:131], v[12:13], v[72:73], v[130:131]
	v_pk_fma_f32 v[134:135], v[12:13], v[80:81], v[134:135]
	v_pk_fma_f32 v[128:129], v[6:7], v[74:75], v[128:129]
	v_pk_fma_f32 v[132:133], v[6:7], v[82:83], v[132:133]
	v_pk_fma_f32 v[130:131], v[14:15], v[74:75], v[130:131]
	v_pk_fma_f32 v[134:135], v[14:15], v[82:83], v[134:135]
	ds_read_b128 v[68:71], v138 offset:6144
	ds_read_b128 v[72:75], v138 offset:6160
	ds_read_b128 v[76:79], v138 offset:6656
	ds_read_b128 v[80:83], v138 offset:6672
	s_waitcnt lgkmcnt(10)
	v_pk_mul_f32 v[112:113], v[108:109], v[100:101] op_sel_hi:[0,1]
	v_pk_mul_f32 v[120:121], v[108:109], v[100:101] op_sel:[1,0]
	v_add_f32_e32 v128, v128, v129
	v_add_f32_e32 v132, v132, v133
	v_add_f32_e32 v129, v130, v131
	v_add_f32_e32 v133, v134, v135
	v_pk_mul_f32 v[114:115], v[108:109], v[102:103] op_sel_hi:[0,1]
	v_pk_mul_f32 v[122:123], v[108:109], v[102:103] op_sel:[1,0]
	v_add_f32_dpp v128, v128, v128 quad_perm:[1,0,3,2] row_mask:0xf bank_mask:0xf bound_ctrl:1
	v_add_f32_dpp v132, v132, v132 quad_perm:[1,0,3,2] row_mask:0xf bank_mask:0xf bound_ctrl:1
	v_add_f32_dpp v129, v129, v129 quad_perm:[1,0,3,2] row_mask:0xf bank_mask:0xf bound_ctrl:1
	v_add_f32_dpp v133, v133, v133 quad_perm:[1,0,3,2] row_mask:0xf bank_mask:0xf bound_ctrl:1
	v_pk_mul_f32 v[116:117], v[108:109], v[104:105] op_sel_hi:[0,1]
	v_pk_mul_f32 v[124:125], v[108:109], v[104:105] op_sel:[1,0]
	v_add_f32_dpp v128, v128, v128 quad_perm:[2,3,0,1] row_mask:0xf bank_mask:0xf bound_ctrl:1
	v_add_f32_dpp v132, v132, v132 quad_perm:[2,3,0,1] row_mask:0xf bank_mask:0xf bound_ctrl:1
	v_add_f32_dpp v129, v129, v129 quad_perm:[2,3,0,1] row_mask:0xf bank_mask:0xf bound_ctrl:1
	v_add_f32_dpp v133, v133, v133 quad_perm:[2,3,0,1] row_mask:0xf bank_mask:0xf bound_ctrl:1
	v_pk_mul_f32 v[118:119], v[108:109], v[106:107] op_sel_hi:[0,1]
	v_pk_mul_f32 v[126:127], v[108:109], v[106:107] op_sel:[1,0]
	v_add_f32_dpp v128, v128, v128 row_half_mirror row_mask:0xf bank_mask:0xf bound_ctrl:1
	v_add_f32_dpp v132, v132, v132 row_half_mirror row_mask:0xf bank_mask:0xf bound_ctrl:1
	v_add_f32_dpp v129, v129, v129 row_half_mirror row_mask:0xf bank_mask:0xf bound_ctrl:1
	v_add_f32_dpp v133, v133, v133 row_half_mirror row_mask:0xf bank_mask:0xf bound_ctrl:1
	ds_read_b128 v[100:103], v138 offset:7168
	ds_read_b128 v[104:107], v138 offset:7184
	s_waitcnt lgkmcnt(11)
	v_pk_fma_f32 v[136:137], v[128:129], v[110:111], v[132:133] op_sel_hi:[1,0,1]
	s_waitcnt lgkmcnt(8)
	v_pk_fma_f32 v[112:113], v[92:93], v[128:129], v[112:113] op_sel_hi:[1,0,1]
	v_pk_fma_f32 v[136:137], v[108:109], v[110:111], v[136:137] op_sel:[0,1,0]
	v_pk_fma_f32 v[120:121], v[92:93], v[128:129], v[120:121] op_sel:[0,1,0]
	ds_read_b64 v[108:109], v139 offset:7424
	ds_read_b64 v[110:111], v140 offset:49216
	s_waitcnt lgkmcnt(8)
	v_pk_fma_f32 v[8:9], v[8:9], v[84:85], v[112:113]
	ds_write_b64 v141, v[136:137] offset:768
	v_pk_fma_f32 v[16:17], v[16:17], v[84:85], v[120:121]
	v_pk_fma_f32 v[114:115], v[94:95], v[128:129], v[114:115] op_sel_hi:[1,0,1]
	v_pk_fma_f32 v[122:123], v[94:95], v[128:129], v[122:123] op_sel:[0,1,0]
	v_pk_fma_f32 v[10:11], v[10:11], v[86:87], v[114:115]
	v_pk_fma_f32 v[18:19], v[18:19], v[86:87], v[122:123]
	v_pk_fma_f32 v[116:117], v[96:97], v[128:129], v[116:117] op_sel_hi:[1,0,1]
	v_pk_fma_f32 v[124:125], v[96:97], v[128:129], v[124:125] op_sel:[0,1,0]
	v_pk_fma_f32 v[4:5], v[4:5], v[88:89], v[116:117]
	v_pk_fma_f32 v[12:13], v[12:13], v[88:89], v[124:125]
	v_pk_fma_f32 v[118:119], v[98:99], v[128:129], v[118:119] op_sel_hi:[1,0,1]
	v_pk_fma_f32 v[126:127], v[98:99], v[128:129], v[126:127] op_sel:[0,1,0]
	v_pk_fma_f32 v[6:7], v[6:7], v[90:91], v[118:119]
	v_pk_fma_f32 v[14:15], v[14:15], v[90:91], v[126:127]
	ds_read_b128 v[92:95], v138 offset:6912
	ds_read_b128 v[96:99], v138 offset:6928
	ds_read_b128 v[84:87], v138 offset:6400
	ds_read_b128 v[88:91], v138 offset:6416
	s_waitcnt lgkmcnt(9)
; __device__ __forceinline__ void rw_load(RwRegs& R, const float* vb, const float* sb, int t, int k0, int vrow0) {
;   const float* vt = vb + t * 384 + k0;
; #pragma unroll
;   for (int q = 0; q < 2; ++q) {
;     R.a[q] = *(const f32x4*)(vt + q * 4);
;     R.wr[q] = *(const f32x4*)(vt + 128 + q * 4);
;     R.w[q] = *(const f32x4*)(vt + 64 + q * 4);
;     R.b[q] = *(const f32x4*)(vt + 192 + q * 4);
;     R.k[q] = *(const f32x4*)(vt + 256 + q * 4);
;   }
;   R.v = *(const f32x2*)(vb + t * 384 + 320 + vrow0);
;   R.sc = *(const f32x4*)(sb + t * 4);
; }
; __device__ __forceinline__ f32x2 rw_step(f32x2 (&S)[2][4], const RwRegs& R) {
;   float sa[2], sy[2];
; #pragma unroll
;   for (int r = 0; r < 2; ++r) {
;     f32x2 a0 = S[r][0] * lo2(R.a[0]);
;     f32x2 a1 = S[r][1] * hi2(R.a[0]);
;     f32x2 y0 = S[r][0] * lo2(R.wr[0]);
;     f32x2 y1 = S[r][1] * hi2(R.wr[0]);
;     a0 += S[r][2] * lo2(R.a[1]);
;     a1 += S[r][3] * hi2(R.a[1]);
;     y0 += S[r][2] * lo2(R.wr[1]);
;     y1 += S[r][3] * hi2(R.wr[1]);
;     a0 += a1; y0 += y1;
;     sa[r] = a0.x + a0.y; sy[r] = y0.x + y0.y;
;   }
;   sa[0] = red8(sa[0]); sa[1] = red8(sa[1]); sy[0] = red8(sy[0]); sy[1] = red8(sy[1]);
;   f32x2 yv;
; #pragma unroll
;   for (int r = 0; r < 2; ++r) {
;     const float vr = r ? R.v.y : R.v.x;
;     const f32x2 sa2 = splat2(sa[r]), vv2 = splat2(vr);
;     S[r][0] = S[r][0] * lo2(R.w[0]) + (sa2 * lo2(R.b[0]) + vv2 * lo2(R.k[0]));
;     S[r][1] = S[r][1] * hi2(R.w[0]) + (sa2 * hi2(R.b[0]) + vv2 * hi2(R.k[0]));
;     S[r][2] = S[r][2] * lo2(R.w[1]) + (sa2 * lo2(R.b[1]) + vv2 * lo2(R.k[1]));
;     S[r][3] = S[r][3] * hi2(R.w[1]) + (sa2 * hi2(R.b[1]) + vv2 * hi2(R.k[1]));
;     const float y = sy[r] + sa[r] * R.sc.x + vr * R.sc.y;
;     if (r) yv.y = y; else yv.x = y;
;   }
;   return yv;
; }
; __device__ __forceinline__ void scan_rwkv(const Params& p, int l, int seq, int h, char* smem, const unsigned* wflags, unsigned wexpect) {
;     ...
;     for (int t = 0; t < nsteps; t += 2) {
;       rw_load(RB, vb, sb, min(t + 1, 15), k0, vrow0);
;       const f32x2 y0v = rw_step(S, RA);
;       *(f32x2*)((part == 0) ? (yb + t * 64 + vrow0) : ydummy) = y0v;
;       SCAN_INTERLEAVE(13, 4);
;       if (t + 1 < nsteps) {
;         rw_load(RA, vb, sb, min(t + 2, 15), k0, vrow0);
;         const f32x2 y1v = rw_step(S, RB);
;         *(f32x2*)((part == 0) ? (yb + (t + 1) * 64 + vrow0) : ydummy) = y1v;
	v_pk_mul_f32 v[128:129], v[8:9], v[68:69]
	v_pk_mul_f32 v[132:133], v[8:9], v[76:77]
	v_pk_mul_f32 v[130:131], v[16:17], v[68:69]
	v_pk_mul_f32 v[134:135], v[16:17], v[76:77]
	v_pk_fma_f32 v[128:129], v[10:11], v[70:71], v[128:129]
	v_pk_fma_f32 v[132:133], v[10:11], v[78:79], v[132:133]
	v_pk_fma_f32 v[130:131], v[18:19], v[70:71], v[130:131]
	v_pk_fma_f32 v[134:135], v[18:19], v[78:79], v[134:135]
	v_pk_fma_f32 v[128:129], v[4:5], v[72:73], v[128:129]
	v_pk_fma_f32 v[132:133], v[4:5], v[80:81], v[132:133]
	v_pk_fma_f32 v[130:131], v[12:13], v[72:73], v[130:131]
	v_pk_fma_f32 v[134:135], v[12:13], v[80:81], v[134:135]
	v_pk_fma_f32 v[128:129], v[6:7], v[74:75], v[128:129]
	v_pk_fma_f32 v[132:133], v[6:7], v[82:83], v[132:133]
	v_pk_fma_f32 v[130:131], v[14:15], v[74:75], v[130:131]
	v_pk_fma_f32 v[134:135], v[14:15], v[82:83], v[134:135]
	ds_read_b128 v[68:71], v138 offset:7680
	ds_read_b128 v[72:75], v138 offset:7696
	ds_read_b128 v[76:79], v138 offset:8192
	ds_read_b128 v[80:83], v138 offset:8208
	s_waitcnt lgkmcnt(10)
	v_pk_mul_f32 v[112:113], v[108:109], v[100:101] op_sel_hi:[0,1]
	v_pk_mul_f32 v[120:121], v[108:109], v[100:101] op_sel:[1,0]
	v_add_f32_e32 v128, v128, v129
	v_add_f32_e32 v132, v132, v133
	v_add_f32_e32 v129, v130, v131
	v_add_f32_e32 v133, v134, v135
	v_pk_mul_f32 v[114:115], v[108:109], v[102:103] op_sel_hi:[0,1]
	v_pk_mul_f32 v[122:123], v[108:109], v[102:103] op_sel:[1,0]
	v_add_f32_dpp v128, v128, v128 quad_perm:[1,0,3,2] row_mask:0xf bank_mask:0xf bound_ctrl:1
	v_add_f32_dpp v132, v132, v132 quad_perm:[1,0,3,2] row_mask:0xf bank_mask:0xf bound_ctrl:1
	v_add_f32_dpp v129, v129, v129 quad_perm:[1,0,3,2] row_mask:0xf bank_mask:0xf bound_ctrl:1
	v_add_f32_dpp v133, v133, v133 quad_perm:[1,0,3,2] row_mask:0xf bank_mask:0xf bound_ctrl:1
	v_pk_mul_f32 v[116:117], v[108:109], v[104:105] op_sel_hi:[0,1]
	v_pk_mul_f32 v[124:125], v[108:109], v[104:105] op_sel:[1,0]
	v_add_f32_dpp v128, v128, v128 quad_perm:[2,3,0,1] row_mask:0xf bank_mask:0xf bound_ctrl:1
	v_add_f32_dpp v132, v132, v132 quad_perm:[2,3,0,1] row_mask:0xf bank_mask:0xf bound_ctrl:1
	v_add_f32_dpp v129, v129, v129 quad_perm:[2,3,0,1] row_mask:0xf bank_mask:0xf bound_ctrl:1
	v_add_f32_dpp v133, v133, v133 quad_perm:[2,3,0,1] row_mask:0xf bank_mask:0xf bound_ctrl:1
	v_pk_mul_f32 v[118:119], v[108:109], v[106:107] op_sel_hi:[0,1]
	v_pk_mul_f32 v[126:127], v[108:109], v[106:107] op_sel:[1,0]
	v_add_f32_dpp v128, v128, v128 row_half_mirror row_mask:0xf bank_mask:0xf bound_ctrl:1
	v_add_f32_dpp v132, v132, v132 row_half_mirror row_mask:0xf bank_mask:0xf bound_ctrl:1
	v_add_f32_dpp v129, v129, v129 row_half_mirror row_mask:0xf bank_mask:0xf bound_ctrl:1
	v_add_f32_dpp v133, v133, v133 row_half_mirror row_mask:0xf bank_mask:0xf bound_ctrl:1
	ds_read_b128 v[100:103], v138 offset:8704
	ds_read_b128 v[104:107], v138 offset:8720
	s_waitcnt lgkmcnt(11)
	v_pk_fma_f32 v[136:137], v[128:129], v[110:111], v[132:133] op_sel_hi:[1,0,1]
	s_waitcnt lgkmcnt(8)
	v_pk_fma_f32 v[112:113], v[92:93], v[128:129], v[112:113] op_sel_hi:[1,0,1]
	v_pk_fma_f32 v[136:137], v[108:109], v[110:111], v[136:137] op_sel:[0,1,0]
	v_pk_fma_f32 v[120:121], v[92:93], v[128:129], v[120:121] op_sel:[0,1,0]
	ds_read_b64 v[108:109], v139 offset:8960
	ds_read_b64 v[110:111], v140 offset:49232
	s_waitcnt lgkmcnt(8)
	v_pk_fma_f32 v[8:9], v[8:9], v[84:85], v[112:113]
	ds_write_b64 v141, v[136:137] offset:1024
	v_pk_fma_f32 v[16:17], v[16:17], v[84:85], v[120:121]
	v_pk_fma_f32 v[114:115], v[94:95], v[128:129], v[114:115] op_sel_hi:[1,0,1]
	v_pk_fma_f32 v[122:123], v[94:95], v[128:129], v[122:123] op_sel:[0,1,0]
	v_pk_fma_f32 v[10:11], v[10:11], v[86:87], v[114:115]
	v_pk_fma_f32 v[18:19], v[18:19], v[86:87], v[122:123]
	v_pk_fma_f32 v[116:117], v[96:97], v[128:129], v[116:117] op_sel_hi:[1,0,1]
	v_pk_fma_f32 v[124:125], v[96:97], v[128:129], v[124:125] op_sel:[0,1,0]
	v_pk_fma_f32 v[4:5], v[4:5], v[88:89], v[116:117]
	v_pk_fma_f32 v[12:13], v[12:13], v[88:89], v[124:125]
	v_pk_fma_f32 v[118:119], v[98:99], v[128:129], v[118:119] op_sel_hi:[1,0,1]
	v_pk_fma_f32 v[126:127], v[98:99], v[128:129], v[126:127] op_sel:[0,1,0]
	v_pk_fma_f32 v[6:7], v[6:7], v[90:91], v[118:119]
	v_pk_fma_f32 v[14:15], v[14:15], v[90:91], v[126:127]
	ds_read_b128 v[92:95], v138 offset:8448
	ds_read_b128 v[96:99], v138 offset:8464
	ds_read_b128 v[84:87], v138 offset:7936
	ds_read_b128 v[88:91], v138 offset:7952
	s_waitcnt lgkmcnt(9)
	v_pk_mul_f32 v[128:129], v[8:9], v[68:69]
	v_pk_mul_f32 v[132:133], v[8:9], v[76:77]
	v_pk_mul_f32 v[130:131], v[16:17], v[68:69]
	v_pk_mul_f32 v[134:135], v[16:17], v[76:77]
	v_pk_fma_f32 v[128:129], v[10:11], v[70:71], v[128:129]
	v_pk_fma_f32 v[132:133], v[10:11], v[78:79], v[132:133]
	v_pk_fma_f32 v[130:131], v[18:19], v[70:71], v[130:131]
	v_pk_fma_f32 v[134:135], v[18:19], v[78:79], v[134:135]
	v_pk_fma_f32 v[128:129], v[4:5], v[72:73], v[128:129]
	v_pk_fma_f32 v[132:133], v[4:5], v[80:81], v[132:133]
	v_pk_fma_f32 v[130:131], v[12:13], v[72:73], v[130:131]
	v_pk_fma_f32 v[134:135], v[12:13], v[80:81], v[134:135]
	v_pk_fma_f32 v[128:129], v[6:7], v[74:75], v[128:129]
	v_pk_fma_f32 v[132:133], v[6:7], v[82:83], v[132:133]
	v_pk_fma_f32 v[130:131], v[14:15], v[74:75], v[130:131]
	v_pk_fma_f32 v[134:135], v[14:15], v[82:83], v[134:135]
	ds_read_b128 v[68:71], v138 offset:9216
	ds_read_b128 v[72:75], v138 offset:9232
	ds_read_b128 v[76:79], v138 offset:9728
	ds_read_b128 v[80:83], v138 offset:9744
	s_waitcnt lgkmcnt(10)
; __device__ __forceinline__ void rw_load(RwRegs& R, const float* vb, const float* sb, int t, int k0, int vrow0) {
;   const float* vt = vb + t * 384 + k0;
; #pragma unroll
;   for (int q = 0; q < 2; ++q) {
;     R.a[q] = *(const f32x4*)(vt + q * 4);
;     R.wr[q] = *(const f32x4*)(vt + 128 + q * 4);
;     R.w[q] = *(const f32x4*)(vt + 64 + q * 4);
;     R.b[q] = *(const f32x4*)(vt + 192 + q * 4);
;     R.k[q] = *(const f32x4*)(vt + 256 + q * 4);
;   }
;   R.v = *(const f32x2*)(vb + t * 384 + 320 + vrow0);
;   R.sc = *(const f32x4*)(sb + t * 4);
; }
; __device__ __forceinline__ f32x2 rw_step(f32x2 (&S)[2][4], const RwRegs& R) {
;   float sa[2], sy[2];
; #pragma unroll
;   for (int r = 0; r < 2; ++r) {
;     f32x2 a0 = S[r][0] * lo2(R.a[0]);
;     f32x2 a1 = S[r][1] * hi2(R.a[0]);
;     f32x2 y0 = S[r][0] * lo2(R.wr[0]);
;     f32x2 y1 = S[r][1] * hi2(R.wr[0]);
;     a0 += S[r][2] * lo2(R.a[1]);
;     a1 += S[r][3] * hi2(R.a[1]);
;     y0 += S[r][2] * lo2(R.wr[1]);
;     y1 += S[r][3] * hi2(R.wr[1]);
;     a0 += a1; y0 += y1;
;     sa[r] = a0.x + a0.y; sy[r] = y0.x + y0.y;
;   }
;   sa[0] = red8(sa[0]); sa[1] = red8(sa[1]); sy[0] = red8(sy[0]); sy[1] = red8(sy[1]);
;   f32x2 yv;
; #pragma unroll
;   for (int r = 0; r < 2; ++r) {
;     const float vr = r ? R.v.y : R.v.x;
;     const f32x2 sa2 = splat2(sa[r]), vv2 = splat2(vr);
;     S[r][0] = S[r][0] * lo2(R.w[0]) + (sa2 * lo2(R.b[0]) + vv2 * lo2(R.k[0]));
;     S[r][1] = S[r][1] * hi2(R.w[0]) + (sa2 * hi2(R.b[0]) + vv2 * hi2(R.k[0]));
;     S[r][2] = S[r][2] * lo2(R.w[1]) + (sa2 * lo2(R.b[1]) + vv2 * lo2(R.k[1]));
;     S[r][3] = S[r][3] * hi2(R.w[1]) + (sa2 * hi2(R.b[1]) + vv2 * hi2(R.k[1]));
;     const float y = sy[r] + sa[r] * R.sc.x + vr * R.sc.y;
;     if (r) yv.y = y; else yv.x = y;
;   }
;   return yv;
; }
; __device__ __forceinline__ void scan_rwkv(const Params& p, int l, int seq, int h, char* smem, const unsigned* wflags, unsigned wexpect) {
;     ...
;     for (int t = 0; t < nsteps; t += 2) {
;       rw_load(RB, vb, sb, min(t + 1, 15), k0, vrow0);
;       const f32x2 y0v = rw_step(S, RA);
;       *(f32x2*)((part == 0) ? (yb + t * 64 + vrow0) : ydummy) = y0v;
;       SCAN_INTERLEAVE(13, 4);
;       if (t + 1 < nsteps) {
;         rw_load(RA, vb, sb, min(t + 2, 15), k0, vrow0);
;         const f32x2 y1v = rw_step(S, RB);
;         *(f32x2*)((part == 0) ? (yb + (t + 1) * 64 + vrow0) : ydummy) = y1v;
	v_pk_mul_f32 v[112:113], v[108:109], v[100:101] op_sel_hi:[0,1]
	v_pk_mul_f32 v[120:121], v[108:109], v[100:101] op_sel:[1,0]
	v_add_f32_e32 v128, v128, v129
	v_add_f32_e32 v132, v132, v133
	v_add_f32_e32 v129, v130, v131
	v_add_f32_e32 v133, v134, v135
	v_pk_mul_f32 v[114:115], v[108:109], v[102:103] op_sel_hi:[0,1]
	v_pk_mul_f32 v[122:123], v[108:109], v[102:103] op_sel:[1,0]
	v_add_f32_dpp v128, v128, v128 quad_perm:[1,0,3,2] row_mask:0xf bank_mask:0xf bound_ctrl:1
	v_add_f32_dpp v132, v132, v132 quad_perm:[1,0,3,2] row_mask:0xf bank_mask:0xf bound_ctrl:1
	v_add_f32_dpp v129, v129, v129 quad_perm:[1,0,3,2] row_mask:0xf bank_mask:0xf bound_ctrl:1
	v_add_f32_dpp v133, v133, v133 quad_perm:[1,0,3,2] row_mask:0xf bank_mask:0xf bound_ctrl:1
	v_pk_mul_f32 v[116:117], v[108:109], v[104:105] op_sel_hi:[0,1]
	v_pk_mul_f32 v[124:125], v[108:109], v[104:105] op_sel:[1,0]
	v_add_f32_dpp v128, v128, v128 quad_perm:[2,3,0,1] row_mask:0xf bank_mask:0xf bound_ctrl:1
	v_add_f32_dpp v132, v132, v132 quad_perm:[2,3,0,1] row_mask:0xf bank_mask:0xf bound_ctrl:1
	v_add_f32_dpp v129, v129, v129 quad_perm:[2,3,0,1] row_mask:0xf bank_mask:0xf bound_ctrl:1
	v_add_f32_dpp v133, v133, v133 quad_perm:[2,3,0,1] row_mask:0xf bank_mask:0xf bound_ctrl:1
	v_pk_mul_f32 v[118:119], v[108:109], v[106:107] op_sel_hi:[0,1]
	v_pk_mul_f32 v[126:127], v[108:109], v[106:107] op_sel:[1,0]
	v_add_f32_dpp v128, v128, v128 row_half_mirror row_mask:0xf bank_mask:0xf bound_ctrl:1
	v_add_f32_dpp v132, v132, v132 row_half_mirror row_mask:0xf bank_mask:0xf bound_ctrl:1
	v_add_f32_dpp v129, v129, v129 row_half_mirror row_mask:0xf bank_mask:0xf bound_ctrl:1
	v_add_f32_dpp v133, v133, v133 row_half_mirror row_mask:0xf bank_mask:0xf bound_ctrl:1
	ds_read_b128 v[100:103], v138 offset:10240
	ds_read_b128 v[104:107], v138 offset:10256
	s_waitcnt lgkmcnt(11)
	v_pk_fma_f32 v[136:137], v[128:129], v[110:111], v[132:133] op_sel_hi:[1,0,1]
	s_waitcnt lgkmcnt(8)
	v_pk_fma_f32 v[112:113], v[92:93], v[128:129], v[112:113] op_sel_hi:[1,0,1]
	v_pk_fma_f32 v[136:137], v[108:109], v[110:111], v[136:137] op_sel:[0,1,0]
	v_pk_fma_f32 v[120:121], v[92:93], v[128:129], v[120:121] op_sel:[0,1,0]
	ds_read_b64 v[108:109], v139 offset:10496
	ds_read_b64 v[110:111], v140 offset:49248
	s_waitcnt lgkmcnt(8)
	v_pk_fma_f32 v[8:9], v[8:9], v[84:85], v[112:113]
	ds_write_b64 v141, v[136:137] offset:1280
	v_pk_fma_f32 v[16:17], v[16:17], v[84:85], v[120:121]
	v_pk_fma_f32 v[114:115], v[94:95], v[128:129], v[114:115] op_sel_hi:[1,0,1]
	v_pk_fma_f32 v[122:123], v[94:95], v[128:129], v[122:123] op_sel:[0,1,0]
	v_pk_fma_f32 v[10:11], v[10:11], v[86:87], v[114:115]
	v_pk_fma_f32 v[18:19], v[18:19], v[86:87], v[122:123]
	v_pk_fma_f32 v[116:117], v[96:97], v[128:129], v[116:117] op_sel_hi:[1,0,1]
	v_pk_fma_f32 v[124:125], v[96:97], v[128:129], v[124:125] op_sel:[0,1,0]
	v_pk_fma_f32 v[4:5], v[4:5], v[88:89], v[116:117]
	v_pk_fma_f32 v[12:13], v[12:13], v[88:89], v[124:125]
	v_pk_fma_f32 v[118:119], v[98:99], v[128:129], v[118:119] op_sel_hi:[1,0,1]
	v_pk_fma_f32 v[126:127], v[98:99], v[128:129], v[126:127] op_sel:[0,1,0]
	v_pk_fma_f32 v[6:7], v[6:7], v[90:91], v[118:119]
	v_pk_fma_f32 v[14:15], v[14:15], v[90:91], v[126:127]
	ds_read_b128 v[92:95], v138 offset:9984
	ds_read_b128 v[96:99], v138 offset:10000
	ds_read_b128 v[84:87], v138 offset:9472
	ds_read_b128 v[88:91], v138 offset:9488
	s_waitcnt lgkmcnt(9)
	v_pk_mul_f32 v[128:129], v[8:9], v[68:69]
	v_pk_mul_f32 v[132:133], v[8:9], v[76:77]
	v_pk_mul_f32 v[130:131], v[16:17], v[68:69]
	v_pk_mul_f32 v[134:135], v[16:17], v[76:77]
	v_pk_fma_f32 v[128:129], v[10:11], v[70:71], v[128:129]
	v_pk_fma_f32 v[132:133], v[10:11], v[78:79], v[132:133]
	v_pk_fma_f32 v[130:131], v[18:19], v[70:71], v[130:131]
	v_pk_fma_f32 v[134:135], v[18:19], v[78:79], v[134:135]
	v_pk_fma_f32 v[128:129], v[4:5], v[72:73], v[128:129]
	v_pk_fma_f32 v[132:133], v[4:5], v[80:81], v[132:133]
	v_pk_fma_f32 v[130:131], v[12:13], v[72:73], v[130:131]
	v_pk_fma_f32 v[134:135], v[12:13], v[80:81], v[134:135]
	v_pk_fma_f32 v[128:129], v[6:7], v[74:75], v[128:129]
	v_pk_fma_f32 v[132:133], v[6:7], v[82:83], v[132:133]
	v_pk_fma_f32 v[130:131], v[14:15], v[74:75], v[130:131]
	v_pk_fma_f32 v[134:135], v[14:15], v[82:83], v[134:135]
	ds_read_b128 v[68:71], v138 offset:10752
	ds_read_b128 v[72:75], v138 offset:10768
	ds_read_b128 v[76:79], v138 offset:11264
	ds_read_b128 v[80:83], v138 offset:11280
	s_waitcnt lgkmcnt(10)
	v_pk_mul_f32 v[112:113], v[108:109], v[100:101] op_sel_hi:[0,1]
	v_pk_mul_f32 v[120:121], v[108:109], v[100:101] op_sel:[1,0]
	v_add_f32_e32 v128, v128, v129
	v_add_f32_e32 v132, v132, v133
	v_add_f32_e32 v129, v130, v131
	v_add_f32_e32 v133, v134, v135
	v_pk_mul_f32 v[114:115], v[108:109], v[102:103] op_sel_hi:[0,1]
	v_pk_mul_f32 v[122:123], v[108:109], v[102:103] op_sel:[1,0]
	v_add_f32_dpp v128, v128, v128 quad_perm:[1,0,3,2] row_mask:0xf bank_mask:0xf bound_ctrl:1
	v_add_f32_dpp v132, v132, v132 quad_perm:[1,0,3,2] row_mask:0xf bank_mask:0xf bound_ctrl:1
	v_add_f32_dpp v129, v129, v129 quad_perm:[1,0,3,2] row_mask:0xf bank_mask:0xf bound_ctrl:1
	v_add_f32_dpp v133, v133, v133 quad_perm:[1,0,3,2] row_mask:0xf bank_mask:0xf bound_ctrl:1
	v_pk_mul_f32 v[116:117], v[108:109], v[104:105] op_sel_hi:[0,1]
	v_pk_mul_f32 v[124:125], v[108:109], v[104:105] op_sel:[1,0]
	v_add_f32_dpp v128, v128, v128 quad_perm:[2,3,0,1] row_mask:0xf bank_mask:0xf bound_ctrl:1
	v_add_f32_dpp v132, v132, v132 quad_perm:[2,3,0,1] row_mask:0xf bank_mask:0xf bound_ctrl:1
	v_add_f32_dpp v129, v129, v129 quad_perm:[2,3,0,1] row_mask:0xf bank_mask:0xf bound_ctrl:1
	v_add_f32_dpp v133, v133, v133 quad_perm:[2,3,0,1] row_mask:0xf bank_mask:0xf bound_ctrl:1
	v_pk_mul_f32 v[118:119], v[108:109], v[106:107] op_sel_hi:[0,1]
	v_pk_mul_f32 v[126:127], v[108:109], v[106:107] op_sel:[1,0]
	v_add_f32_dpp v128, v128, v128 row_half_mirror row_mask:0xf bank_mask:0xf bound_ctrl:1
	v_add_f32_dpp v132, v132, v132 row_half_mirror row_mask:0xf bank_mask:0xf bound_ctrl:1
	v_add_f32_dpp v129, v129, v129 row_half_mirror row_mask:0xf bank_mask:0xf bound_ctrl:1
	v_add_f32_dpp v133, v133, v133 row_half_mirror row_mask:0xf bank_mask:0xf bound_ctrl:1
	ds_read_b128 v[100:103], v138 offset:11776
	ds_read_b128 v[104:107], v138 offset:11792
	s_waitcnt lgkmcnt(11)
; __device__ __forceinline__ void rw_load(RwRegs& R, const float* vb, const float* sb, int t, int k0, int vrow0) {
;   const float* vt = vb + t * 384 + k0;
; #pragma unroll
;   for (int q = 0; q < 2; ++q) {
;     R.a[q] = *(const f32x4*)(vt + q * 4);
;     R.wr[q] = *(const f32x4*)(vt + 128 + q * 4);
;     R.w[q] = *(const f32x4*)(vt + 64 + q * 4);
;     R.b[q] = *(const f32x4*)(vt + 192 + q * 4);
;     R.k[q] = *(const f32x4*)(vt + 256 + q * 4);
;   }
;   R.v = *(const f32x2*)(vb + t * 384 + 320 + vrow0);
;   R.sc = *(const f32x4*)(sb + t * 4);
; }
; __device__ __forceinline__ f32x2 rw_step(f32x2 (&S)[2][4], const RwRegs& R) {
;   float sa[2], sy[2];
; #pragma unroll
;   for (int r = 0; r < 2; ++r) {
;     f32x2 a0 = S[r][0] * lo2(R.a[0]);
;     f32x2 a1 = S[r][1] * hi2(R.a[0]);
;     f32x2 y0 = S[r][0] * lo2(R.wr[0]);
;     f32x2 y1 = S[r][1] * hi2(R.wr[0]);
;     a0 += S[r][2] * lo2(R.a[1]);
;     a1 += S[r][3] * hi2(R.a[1]);
;     y0 += S[r][2] * lo2(R.wr[1]);
;     y1 += S[r][3] * hi2(R.wr[1]);
;     a0 += a1; y0 += y1;
;     sa[r] = a0.x + a0.y; sy[r] = y0.x + y0.y;
;   }
;   sa[0] = red8(sa[0]); sa[1] = red8(sa[1]); sy[0] = red8(sy[0]); sy[1] = red8(sy[1]);
;   f32x2 yv;
; #pragma unroll
;   for (int r = 0; r < 2; ++r) {
;     const float vr = r ? R.v.y : R.v.x;
;     const f32x2 sa2 = splat2(sa[r]), vv2 = splat2(vr);
;     S[r][0] = S[r][0] * lo2(R.w[0]) + (sa2 * lo2(R.b[0]) + vv2 * lo2(R.k[0]));
;     S[r][1] = S[r][1] * hi2(R.w[0]) + (sa2 * hi2(R.b[0]) + vv2 * hi2(R.k[0]));
;     S[r][2] = S[r][2] * lo2(R.w[1]) + (sa2 * lo2(R.b[1]) + vv2 * lo2(R.k[1]));
;     S[r][3] = S[r][3] * hi2(R.w[1]) + (sa2 * hi2(R.b[1]) + vv2 * hi2(R.k[1]));
;     const float y = sy[r] + sa[r] * R.sc.x + vr * R.sc.y;
;     if (r) yv.y = y; else yv.x = y;
;   }
;   return yv;
; }
; __device__ __forceinline__ void scan_rwkv(const Params& p, int l, int seq, int h, char* smem, const unsigned* wflags, unsigned wexpect) {
;     ...
;     for (int t = 0; t < nsteps; t += 2) {
;       rw_load(RB, vb, sb, min(t + 1, 15), k0, vrow0);
;       const f32x2 y0v = rw_step(S, RA);
;       *(f32x2*)((part == 0) ? (yb + t * 64 + vrow0) : ydummy) = y0v;
;       SCAN_INTERLEAVE(13, 4);
;       if (t + 1 < nsteps) {
;         rw_load(RA, vb, sb, min(t + 2, 15), k0, vrow0);
;         const f32x2 y1v = rw_step(S, RB);
;         *(f32x2*)((part == 0) ? (yb + (t + 1) * 64 + vrow0) : ydummy) = y1v;
	v_pk_fma_f32 v[136:137], v[128:129], v[110:111], v[132:133] op_sel_hi:[1,0,1]
	s_waitcnt lgkmcnt(8)
	v_pk_fma_f32 v[112:113], v[92:93], v[128:129], v[112:113] op_sel_hi:[1,0,1]
	v_pk_fma_f32 v[136:137], v[108:109], v[110:111], v[136:137] op_sel:[0,1,0]
	v_pk_fma_f32 v[120:121], v[92:93], v[128:129], v[120:121] op_sel:[0,1,0]
	ds_read_b64 v[108:109], v139 offset:12032
	ds_read_b64 v[110:111], v140 offset:49264
	s_waitcnt lgkmcnt(8)
	v_pk_fma_f32 v[8:9], v[8:9], v[84:85], v[112:113]
	ds_write_b64 v141, v[136:137] offset:1536
	v_pk_fma_f32 v[16:17], v[16:17], v[84:85], v[120:121]
	v_pk_fma_f32 v[114:115], v[94:95], v[128:129], v[114:115] op_sel_hi:[1,0,1]
	v_pk_fma_f32 v[122:123], v[94:95], v[128:129], v[122:123] op_sel:[0,1,0]
	v_pk_fma_f32 v[10:11], v[10:11], v[86:87], v[114:115]
	v_pk_fma_f32 v[18:19], v[18:19], v[86:87], v[122:123]
	v_pk_fma_f32 v[116:117], v[96:97], v[128:129], v[116:117] op_sel_hi:[1,0,1]
	v_pk_fma_f32 v[124:125], v[96:97], v[128:129], v[124:125] op_sel:[0,1,0]
	v_pk_fma_f32 v[4:5], v[4:5], v[88:89], v[116:117]
	v_pk_fma_f32 v[12:13], v[12:13], v[88:89], v[124:125]
	v_pk_fma_f32 v[118:119], v[98:99], v[128:129], v[118:119] op_sel_hi:[1,0,1]
	v_pk_fma_f32 v[126:127], v[98:99], v[128:129], v[126:127] op_sel:[0,1,0]
	v_pk_fma_f32 v[6:7], v[6:7], v[90:91], v[118:119]
	v_pk_fma_f32 v[14:15], v[14:15], v[90:91], v[126:127]
	ds_read_b128 v[92:95], v138 offset:11520
	ds_read_b128 v[96:99], v138 offset:11536
	ds_read_b128 v[84:87], v138 offset:11008
	ds_read_b128 v[88:91], v138 offset:11024
	s_waitcnt lgkmcnt(9)
	v_pk_mul_f32 v[128:129], v[8:9], v[68:69]
	v_pk_mul_f32 v[132:133], v[8:9], v[76:77]
	v_pk_mul_f32 v[130:131], v[16:17], v[68:69]
	v_pk_mul_f32 v[134:135], v[16:17], v[76:77]
	v_pk_fma_f32 v[128:129], v[10:11], v[70:71], v[128:129]
	v_pk_fma_f32 v[132:133], v[10:11], v[78:79], v[132:133]
	v_pk_fma_f32 v[130:131], v[18:19], v[70:71], v[130:131]
	v_pk_fma_f32 v[134:135], v[18:19], v[78:79], v[134:135]
	v_pk_fma_f32 v[128:129], v[4:5], v[72:73], v[128:129]
	v_pk_fma_f32 v[132:133], v[4:5], v[80:81], v[132:133]
	v_pk_fma_f32 v[130:131], v[12:13], v[72:73], v[130:131]
	v_pk_fma_f32 v[134:135], v[12:13], v[80:81], v[134:135]
	v_pk_fma_f32 v[128:129], v[6:7], v[74:75], v[128:129]
	v_pk_fma_f32 v[132:133], v[6:7], v[82:83], v[132:133]
	v_pk_fma_f32 v[130:131], v[14:15], v[74:75], v[130:131]
	v_pk_fma_f32 v[134:135], v[14:15], v[82:83], v[134:135]
	ds_read_b128 v[68:71], v138 offset:12288
	ds_read_b128 v[72:75], v138 offset:12304
	ds_read_b128 v[76:79], v138 offset:12800
	ds_read_b128 v[80:83], v138 offset:12816
	s_waitcnt lgkmcnt(10)
	v_pk_mul_f32 v[112:113], v[108:109], v[100:101] op_sel_hi:[0,1]
	v_pk_mul_f32 v[120:121], v[108:109], v[100:101] op_sel:[1,0]
	v_add_f32_e32 v128, v128, v129
	v_add_f32_e32 v132, v132, v133
	v_add_f32_e32 v129, v130, v131
	v_add_f32_e32 v133, v134, v135
	v_pk_mul_f32 v[114:115], v[108:109], v[102:103] op_sel_hi:[0,1]
	v_pk_mul_f32 v[122:123], v[108:109], v[102:103] op_sel:[1,0]
	v_add_f32_dpp v128, v128, v128 quad_perm:[1,0,3,2] row_mask:0xf bank_mask:0xf bound_ctrl:1
	v_add_f32_dpp v132, v132, v132 quad_perm:[1,0,3,2] row_mask:0xf bank_mask:0xf bound_ctrl:1
	v_add_f32_dpp v129, v129, v129 quad_perm:[1,0,3,2] row_mask:0xf bank_mask:0xf bound_ctrl:1
	v_add_f32_dpp v133, v133, v133 quad_perm:[1,0,3,2] row_mask:0xf bank_mask:0xf bound_ctrl:1
	v_pk_mul_f32 v[116:117], v[108:109], v[104:105] op_sel_hi:[0,1]
	v_pk_mul_f32 v[124:125], v[108:109], v[104:105] op_sel:[1,0]
	v_add_f32_dpp v128, v128, v128 quad_perm:[2,3,0,1] row_mask:0xf bank_mask:0xf bound_ctrl:1
	v_add_f32_dpp v132, v132, v132 quad_perm:[2,3,0,1] row_mask:0xf bank_mask:0xf bound_ctrl:1
	v_add_f32_dpp v129, v129, v129 quad_perm:[2,3,0,1] row_mask:0xf bank_mask:0xf bound_ctrl:1
	v_add_f32_dpp v133, v133, v133 quad_perm:[2,3,0,1] row_mask:0xf bank_mask:0xf bound_ctrl:1
	v_pk_mul_f32 v[118:119], v[108:109], v[106:107] op_sel_hi:[0,1]
	v_pk_mul_f32 v[126:127], v[108:109], v[106:107] op_sel:[1,0]
	v_add_f32_dpp v128, v128, v128 row_half_mirror row_mask:0xf bank_mask:0xf bound_ctrl:1
	v_add_f32_dpp v132, v132, v132 row_half_mirror row_mask:0xf bank_mask:0xf bound_ctrl:1
	v_add_f32_dpp v129, v129, v129 row_half_mirror row_mask:0xf bank_mask:0xf bound_ctrl:1
	v_add_f32_dpp v133, v133, v133 row_half_mirror row_mask:0xf bank_mask:0xf bound_ctrl:1
	ds_read_b128 v[100:103], v138 offset:13312
	ds_read_b128 v[104:107], v138 offset:13328
	s_waitcnt lgkmcnt(11)
	v_pk_fma_f32 v[136:137], v[128:129], v[110:111], v[132:133] op_sel_hi:[1,0,1]
	s_waitcnt lgkmcnt(8)
	v_pk_fma_f32 v[112:113], v[92:93], v[128:129], v[112:113] op_sel_hi:[1,0,1]
	v_pk_fma_f32 v[136:137], v[108:109], v[110:111], v[136:137] op_sel:[0,1,0]
	v_pk_fma_f32 v[120:121], v[92:93], v[128:129], v[120:121] op_sel:[0,1,0]
	ds_read_b64 v[108:109], v139 offset:13568
	ds_read_b64 v[110:111], v140 offset:49280
	s_waitcnt lgkmcnt(8)
	v_pk_fma_f32 v[8:9], v[8:9], v[84:85], v[112:113]
	ds_write_b64 v141, v[136:137] offset:1792
	v_pk_fma_f32 v[16:17], v[16:17], v[84:85], v[120:121]
	v_pk_fma_f32 v[114:115], v[94:95], v[128:129], v[114:115] op_sel_hi:[1,0,1]
	v_pk_fma_f32 v[122:123], v[94:95], v[128:129], v[122:123] op_sel:[0,1,0]
	v_pk_fma_f32 v[10:11], v[10:11], v[86:87], v[114:115]
	v_pk_fma_f32 v[18:19], v[18:19], v[86:87], v[122:123]
	v_pk_fma_f32 v[116:117], v[96:97], v[128:129], v[116:117] op_sel_hi:[1,0,1]
	v_pk_fma_f32 v[124:125], v[96:97], v[128:129], v[124:125] op_sel:[0,1,0]
	v_pk_fma_f32 v[4:5], v[4:5], v[88:89], v[116:117]
	v_pk_fma_f32 v[12:13], v[12:13], v[88:89], v[124:125]
	v_pk_fma_f32 v[118:119], v[98:99], v[128:129], v[118:119] op_sel_hi:[1,0,1]
	v_pk_fma_f32 v[126:127], v[98:99], v[128:129], v[126:127] op_sel:[0,1,0]
	v_pk_fma_f32 v[6:7], v[6:7], v[90:91], v[118:119]
	v_pk_fma_f32 v[14:15], v[14:15], v[90:91], v[126:127]
	ds_read_b128 v[92:95], v138 offset:13056
	ds_read_b128 v[96:99], v138 offset:13072
	ds_read_b128 v[84:87], v138 offset:12544
	ds_read_b128 v[88:91], v138 offset:12560
	s_waitcnt lgkmcnt(9)
; __device__ __forceinline__ void rw_load(RwRegs& R, const float* vb, const float* sb, int t, int k0, int vrow0) {
;   const float* vt = vb + t * 384 + k0;
; #pragma unroll
;   for (int q = 0; q < 2; ++q) {
;     R.a[q] = *(const f32x4*)(vt + q * 4);
;     R.wr[q] = *(const f32x4*)(vt + 128 + q * 4);
;     R.w[q] = *(const f32x4*)(vt + 64 + q * 4);
;     R.b[q] = *(const f32x4*)(vt + 192 + q * 4);
;     R.k[q] = *(const f32x4*)(vt + 256 + q * 4);
;   }
;   R.v = *(const f32x2*)(vb + t * 384 + 320 + vrow0);
;   R.sc = *(const f32x4*)(sb + t * 4);
; }
; __device__ __forceinline__ f32x2 rw_step(f32x2 (&S)[2][4], const RwRegs& R) {
;   float sa[2], sy[2];
; #pragma unroll
;   for (int r = 0; r < 2; ++r) {
;     f32x2 a0 = S[r][0] * lo2(R.a[0]);
;     f32x2 a1 = S[r][1] * hi2(R.a[0]);
;     f32x2 y0 = S[r][0] * lo2(R.wr[0]);
;     f32x2 y1 = S[r][1] * hi2(R.wr[0]);
;     a0 += S[r][2] * lo2(R.a[1]);
;     a1 += S[r][3] * hi2(R.a[1]);
;     y0 += S[r][2] * lo2(R.wr[1]);
;     y1 += S[r][3] * hi2(R.wr[1]);
;     a0 += a1; y0 += y1;
;     sa[r] = a0.x + a0.y; sy[r] = y0.x + y0.y;
;   }
;   sa[0] = red8(sa[0]); sa[1] = red8(sa[1]); sy[0] = red8(sy[0]); sy[1] = red8(sy[1]);
;   f32x2 yv;
; #pragma unroll
;   for (int r = 0; r < 2; ++r) {
;     const float vr = r ? R.v.y : R.v.x;
;     const f32x2 sa2 = splat2(sa[r]), vv2 = splat2(vr);
;     S[r][0] = S[r][0] * lo2(R.w[0]) + (sa2 * lo2(R.b[0]) + vv2 * lo2(R.k[0]));
;     S[r][1] = S[r][1] * hi2(R.w[0]) + (sa2 * hi2(R.b[0]) + vv2 * hi2(R.k[0]));
;     S[r][2] = S[r][2] * lo2(R.w[1]) + (sa2 * lo2(R.b[1]) + vv2 * lo2(R.k[1]));
;     S[r][3] = S[r][3] * hi2(R.w[1]) + (sa2 * hi2(R.b[1]) + vv2 * hi2(R.k[1]));
;     const float y = sy[r] + sa[r] * R.sc.x + vr * R.sc.y;
;     if (r) yv.y = y; else yv.x = y;
;   }
;   return yv;
; }
; __device__ __forceinline__ void scan_rwkv(const Params& p, int l, int seq, int h, char* smem, const unsigned* wflags, unsigned wexpect) {
;     ...
;     for (int t = 0; t < nsteps; t += 2) {
;       rw_load(RB, vb, sb, min(t + 1, 15), k0, vrow0);
;       const f32x2 y0v = rw_step(S, RA);
;       *(f32x2*)((part == 0) ? (yb + t * 64 + vrow0) : ydummy) = y0v;
;       SCAN_INTERLEAVE(13, 4);
;       if (t + 1 < nsteps) {
;         rw_load(RA, vb, sb, min(t + 2, 15), k0, vrow0);
;         const f32x2 y1v = rw_step(S, RB);
;         *(f32x2*)((part == 0) ? (yb + (t + 1) * 64 + vrow0) : ydummy) = y1v;
	v_pk_mul_f32 v[128:129], v[8:9], v[68:69]
	v_pk_mul_f32 v[132:133], v[8:9], v[76:77]
	v_pk_mul_f32 v[130:131], v[16:17], v[68:69]
	v_pk_mul_f32 v[134:135], v[16:17], v[76:77]
	v_pk_fma_f32 v[128:129], v[10:11], v[70:71], v[128:129]
	v_pk_fma_f32 v[132:133], v[10:11], v[78:79], v[132:133]
	v_pk_fma_f32 v[130:131], v[18:19], v[70:71], v[130:131]
	v_pk_fma_f32 v[134:135], v[18:19], v[78:79], v[134:135]
	v_pk_fma_f32 v[128:129], v[4:5], v[72:73], v[128:129]
	v_pk_fma_f32 v[132:133], v[4:5], v[80:81], v[132:133]
	v_pk_fma_f32 v[130:131], v[12:13], v[72:73], v[130:131]
	v_pk_fma_f32 v[134:135], v[12:13], v[80:81], v[134:135]
	v_pk_fma_f32 v[128:129], v[6:7], v[74:75], v[128:129]
	v_pk_fma_f32 v[132:133], v[6:7], v[82:83], v[132:133]
	v_pk_fma_f32 v[130:131], v[14:15], v[74:75], v[130:131]
	v_pk_fma_f32 v[134:135], v[14:15], v[82:83], v[134:135]
	ds_read_b128 v[68:71], v138 offset:13824
	ds_read_b128 v[72:75], v138 offset:13840
	ds_read_b128 v[76:79], v138 offset:14336
	ds_read_b128 v[80:83], v138 offset:14352
	s_waitcnt lgkmcnt(10)
	v_pk_mul_f32 v[112:113], v[108:109], v[100:101] op_sel_hi:[0,1]
	v_pk_mul_f32 v[120:121], v[108:109], v[100:101] op_sel:[1,0]
	v_add_f32_e32 v128, v128, v129
	v_add_f32_e32 v132, v132, v133
	v_add_f32_e32 v129, v130, v131
	v_add_f32_e32 v133, v134, v135
	v_pk_mul_f32 v[114:115], v[108:109], v[102:103] op_sel_hi:[0,1]
	v_pk_mul_f32 v[122:123], v[108:109], v[102:103] op_sel:[1,0]
	v_add_f32_dpp v128, v128, v128 quad_perm:[1,0,3,2] row_mask:0xf bank_mask:0xf bound_ctrl:1
	v_add_f32_dpp v132, v132, v132 quad_perm:[1,0,3,2] row_mask:0xf bank_mask:0xf bound_ctrl:1
	v_add_f32_dpp v129, v129, v129 quad_perm:[1,0,3,2] row_mask:0xf bank_mask:0xf bound_ctrl:1
	v_add_f32_dpp v133, v133, v133 quad_perm:[1,0,3,2] row_mask:0xf bank_mask:0xf bound_ctrl:1
	v_pk_mul_f32 v[116:117], v[108:109], v[104:105] op_sel_hi:[0,1]
	v_pk_mul_f32 v[124:125], v[108:109], v[104:105] op_sel:[1,0]
	v_add_f32_dpp v128, v128, v128 quad_perm:[2,3,0,1] row_mask:0xf bank_mask:0xf bound_ctrl:1
	v_add_f32_dpp v132, v132, v132 quad_perm:[2,3,0,1] row_mask:0xf bank_mask:0xf bound_ctrl:1
	v_add_f32_dpp v129, v129, v129 quad_perm:[2,3,0,1] row_mask:0xf bank_mask:0xf bound_ctrl:1
	v_add_f32_dpp v133, v133, v133 quad_perm:[2,3,0,1] row_mask:0xf bank_mask:0xf bound_ctrl:1
	v_pk_mul_f32 v[118:119], v[108:109], v[106:107] op_sel_hi:[0,1]
	v_pk_mul_f32 v[126:127], v[108:109], v[106:107] op_sel:[1,0]
	v_add_f32_dpp v128, v128, v128 row_half_mirror row_mask:0xf bank_mask:0xf bound_ctrl:1
	v_add_f32_dpp v132, v132, v132 row_half_mirror row_mask:0xf bank_mask:0xf bound_ctrl:1
	v_add_f32_dpp v129, v129, v129 row_half_mirror row_mask:0xf bank_mask:0xf bound_ctrl:1
	v_add_f32_dpp v133, v133, v133 row_half_mirror row_mask:0xf bank_mask:0xf bound_ctrl:1
	ds_read_b128 v[100:103], v138 offset:14848
	ds_read_b128 v[104:107], v138 offset:14864
	s_waitcnt lgkmcnt(11)
	v_pk_fma_f32 v[136:137], v[128:129], v[110:111], v[132:133] op_sel_hi:[1,0,1]
	s_waitcnt lgkmcnt(8)
	v_pk_fma_f32 v[112:113], v[92:93], v[128:129], v[112:113] op_sel_hi:[1,0,1]
	v_pk_fma_f32 v[136:137], v[108:109], v[110:111], v[136:137] op_sel:[0,1,0]
	v_pk_fma_f32 v[120:121], v[92:93], v[128:129], v[120:121] op_sel:[0,1,0]
	ds_read_b64 v[108:109], v139 offset:15104
	ds_read_b64 v[110:111], v140 offset:49296
	s_waitcnt lgkmcnt(8)
	v_pk_fma_f32 v[8:9], v[8:9], v[84:85], v[112:113]
	ds_write_b64 v141, v[136:137] offset:2048
	v_pk_fma_f32 v[16:17], v[16:17], v[84:85], v[120:121]
	v_pk_fma_f32 v[114:115], v[94:95], v[128:129], v[114:115] op_sel_hi:[1,0,1]
	v_pk_fma_f32 v[122:123], v[94:95], v[128:129], v[122:123] op_sel:[0,1,0]
	v_pk_fma_f32 v[10:11], v[10:11], v[86:87], v[114:115]
	v_pk_fma_f32 v[18:19], v[18:19], v[86:87], v[122:123]
	v_pk_fma_f32 v[116:117], v[96:97], v[128:129], v[116:117] op_sel_hi:[1,0,1]
	v_pk_fma_f32 v[124:125], v[96:97], v[128:129], v[124:125] op_sel:[0,1,0]
	v_pk_fma_f32 v[4:5], v[4:5], v[88:89], v[116:117]
	v_pk_fma_f32 v[12:13], v[12:13], v[88:89], v[124:125]
	v_pk_fma_f32 v[118:119], v[98:99], v[128:129], v[118:119] op_sel_hi:[1,0,1]
	v_pk_fma_f32 v[126:127], v[98:99], v[128:129], v[126:127] op_sel:[0,1,0]
	v_pk_fma_f32 v[6:7], v[6:7], v[90:91], v[118:119]
	v_pk_fma_f32 v[14:15], v[14:15], v[90:91], v[126:127]
	ds_read_b128 v[92:95], v138 offset:14592
	ds_read_b128 v[96:99], v138 offset:14608
	ds_read_b128 v[84:87], v138 offset:14080
	ds_read_b128 v[88:91], v138 offset:14096
	s_waitcnt lgkmcnt(9)
	v_pk_mul_f32 v[128:129], v[8:9], v[68:69]
	v_pk_mul_f32 v[132:133], v[8:9], v[76:77]
	v_pk_mul_f32 v[130:131], v[16:17], v[68:69]
	v_pk_mul_f32 v[134:135], v[16:17], v[76:77]
	v_pk_fma_f32 v[128:129], v[10:11], v[70:71], v[128:129]
	v_pk_fma_f32 v[132:133], v[10:11], v[78:79], v[132:133]
	v_pk_fma_f32 v[130:131], v[18:19], v[70:71], v[130:131]
	v_pk_fma_f32 v[134:135], v[18:19], v[78:79], v[134:135]
	v_pk_fma_f32 v[128:129], v[4:5], v[72:73], v[128:129]
	v_pk_fma_f32 v[132:133], v[4:5], v[80:81], v[132:133]
	v_pk_fma_f32 v[130:131], v[12:13], v[72:73], v[130:131]
	v_pk_fma_f32 v[134:135], v[12:13], v[80:81], v[134:135]
	v_pk_fma_f32 v[128:129], v[6:7], v[74:75], v[128:129]
	v_pk_fma_f32 v[132:133], v[6:7], v[82:83], v[132:133]
	v_pk_fma_f32 v[130:131], v[14:15], v[74:75], v[130:131]
	v_pk_fma_f32 v[134:135], v[14:15], v[82:83], v[134:135]
	ds_read_b128 v[68:71], v138 offset:15360
	ds_read_b128 v[72:75], v138 offset:15376
	ds_read_b128 v[76:79], v138 offset:15872
	ds_read_b128 v[80:83], v138 offset:15888
	s_waitcnt lgkmcnt(10)
; __device__ __forceinline__ void rw_load(RwRegs& R, const float* vb, const float* sb, int t, int k0, int vrow0) {
;   const float* vt = vb + t * 384 + k0;
; #pragma unroll
;   for (int q = 0; q < 2; ++q) {
;     R.a[q] = *(const f32x4*)(vt + q * 4);
;     R.wr[q] = *(const f32x4*)(vt + 128 + q * 4);
;     R.w[q] = *(const f32x4*)(vt + 64 + q * 4);
;     R.b[q] = *(const f32x4*)(vt + 192 + q * 4);
;     R.k[q] = *(const f32x4*)(vt + 256 + q * 4);
;   }
;   R.v = *(const f32x2*)(vb + t * 384 + 320 + vrow0);
;   R.sc = *(const f32x4*)(sb + t * 4);
; }
; __device__ __forceinline__ f32x2 rw_step(f32x2 (&S)[2][4], const RwRegs& R) {
;   float sa[2], sy[2];
; #pragma unroll
;   for (int r = 0; r < 2; ++r) {
;     f32x2 a0 = S[r][0] * lo2(R.a[0]);
;     f32x2 a1 = S[r][1] * hi2(R.a[0]);
;     f32x2 y0 = S[r][0] * lo2(R.wr[0]);
;     f32x2 y1 = S[r][1] * hi2(R.wr[0]);
;     a0 += S[r][2] * lo2(R.a[1]);
;     a1 += S[r][3] * hi2(R.a[1]);
;     y0 += S[r][2] * lo2(R.wr[1]);
;     y1 += S[r][3] * hi2(R.wr[1]);
;     a0 += a1; y0 += y1;
;     sa[r] = a0.x + a0.y; sy[r] = y0.x + y0.y;
;   }
;   sa[0] = red8(sa[0]); sa[1] = red8(sa[1]); sy[0] = red8(sy[0]); sy[1] = red8(sy[1]);
;   f32x2 yv;
; #pragma unroll
;   for (int r = 0; r < 2; ++r) {
;     const float vr = r ? R.v.y : R.v.x;
;     const f32x2 sa2 = splat2(sa[r]), vv2 = splat2(vr);
;     S[r][0] = S[r][0] * lo2(R.w[0]) + (sa2 * lo2(R.b[0]) + vv2 * lo2(R.k[0]));
;     S[r][1] = S[r][1] * hi2(R.w[0]) + (sa2 * hi2(R.b[0]) + vv2 * hi2(R.k[0]));
;     S[r][2] = S[r][2] * lo2(R.w[1]) + (sa2 * lo2(R.b[1]) + vv2 * lo2(R.k[1]));
;     S[r][3] = S[r][3] * hi2(R.w[1]) + (sa2 * hi2(R.b[1]) + vv2 * hi2(R.k[1]));
;     const float y = sy[r] + sa[r] * R.sc.x + vr * R.sc.y;
;     if (r) yv.y = y; else yv.x = y;
;   }
;   return yv;
; }
; __device__ __forceinline__ void scan_rwkv(const Params& p, int l, int seq, int h, char* smem, const unsigned* wflags, unsigned wexpect) {
;     ...
;     for (int t = 0; t < nsteps; t += 2) {
;       rw_load(RB, vb, sb, min(t + 1, 15), k0, vrow0);
;       const f32x2 y0v = rw_step(S, RA);
;       *(f32x2*)((part == 0) ? (yb + t * 64 + vrow0) : ydummy) = y0v;
;       SCAN_INTERLEAVE(13, 4);
;       if (t + 1 < nsteps) {
;         rw_load(RA, vb, sb, min(t + 2, 15), k0, vrow0);
;         const f32x2 y1v = rw_step(S, RB);
;         *(f32x2*)((part == 0) ? (yb + (t + 1) * 64 + vrow0) : ydummy) = y1v;
	v_pk_mul_f32 v[112:113], v[108:109], v[100:101] op_sel_hi:[0,1]
	v_pk_mul_f32 v[120:121], v[108:109], v[100:101] op_sel:[1,0]
	v_add_f32_e32 v128, v128, v129
	v_add_f32_e32 v132, v132, v133
	v_add_f32_e32 v129, v130, v131
	v_add_f32_e32 v133, v134, v135
	v_pk_mul_f32 v[114:115], v[108:109], v[102:103] op_sel_hi:[0,1]
	v_pk_mul_f32 v[122:123], v[108:109], v[102:103] op_sel:[1,0]
	v_add_f32_dpp v128, v128, v128 quad_perm:[1,0,3,2] row_mask:0xf bank_mask:0xf bound_ctrl:1
	v_add_f32_dpp v132, v132, v132 quad_perm:[1,0,3,2] row_mask:0xf bank_mask:0xf bound_ctrl:1
	v_add_f32_dpp v129, v129, v129 quad_perm:[1,0,3,2] row_mask:0xf bank_mask:0xf bound_ctrl:1
	v_add_f32_dpp v133, v133, v133 quad_perm:[1,0,3,2] row_mask:0xf bank_mask:0xf bound_ctrl:1
	v_pk_mul_f32 v[116:117], v[108:109], v[104:105] op_sel_hi:[0,1]
	v_pk_mul_f32 v[124:125], v[108:109], v[104:105] op_sel:[1,0]
	v_add_f32_dpp v128, v128, v128 quad_perm:[2,3,0,1] row_mask:0xf bank_mask:0xf bound_ctrl:1
	v_add_f32_dpp v132, v132, v132 quad_perm:[2,3,0,1] row_mask:0xf bank_mask:0xf bound_ctrl:1
	v_add_f32_dpp v129, v129, v129 quad_perm:[2,3,0,1] row_mask:0xf bank_mask:0xf bound_ctrl:1
	v_add_f32_dpp v133, v133, v133 quad_perm:[2,3,0,1] row_mask:0xf bank_mask:0xf bound_ctrl:1
	v_pk_mul_f32 v[118:119], v[108:109], v[106:107] op_sel_hi:[0,1]
	v_pk_mul_f32 v[126:127], v[108:109], v[106:107] op_sel:[1,0]
	v_add_f32_dpp v128, v128, v128 row_half_mirror row_mask:0xf bank_mask:0xf bound_ctrl:1
	v_add_f32_dpp v132, v132, v132 row_half_mirror row_mask:0xf bank_mask:0xf bound_ctrl:1
	v_add_f32_dpp v129, v129, v129 row_half_mirror row_mask:0xf bank_mask:0xf bound_ctrl:1
	v_add_f32_dpp v133, v133, v133 row_half_mirror row_mask:0xf bank_mask:0xf bound_ctrl:1
	ds_read_b128 v[100:103], v138 offset:16384
	ds_read_b128 v[104:107], v138 offset:16400
	s_waitcnt lgkmcnt(11)
	v_pk_fma_f32 v[136:137], v[128:129], v[110:111], v[132:133] op_sel_hi:[1,0,1]
	s_waitcnt lgkmcnt(8)
	v_pk_fma_f32 v[112:113], v[92:93], v[128:129], v[112:113] op_sel_hi:[1,0,1]
	v_pk_fma_f32 v[136:137], v[108:109], v[110:111], v[136:137] op_sel:[0,1,0]
	v_pk_fma_f32 v[120:121], v[92:93], v[128:129], v[120:121] op_sel:[0,1,0]
	ds_read_b64 v[108:109], v139 offset:16640
	ds_read_b64 v[110:111], v140 offset:49312
	s_waitcnt lgkmcnt(8)
	v_pk_fma_f32 v[8:9], v[8:9], v[84:85], v[112:113]
	ds_write_b64 v141, v[136:137] offset:2304
	v_pk_fma_f32 v[16:17], v[16:17], v[84:85], v[120:121]
	v_pk_fma_f32 v[114:115], v[94:95], v[128:129], v[114:115] op_sel_hi:[1,0,1]
	v_pk_fma_f32 v[122:123], v[94:95], v[128:129], v[122:123] op_sel:[0,1,0]
	v_pk_fma_f32 v[10:11], v[10:11], v[86:87], v[114:115]
	v_pk_fma_f32 v[18:19], v[18:19], v[86:87], v[122:123]
	v_pk_fma_f32 v[116:117], v[96:97], v[128:129], v[116:117] op_sel_hi:[1,0,1]
	v_pk_fma_f32 v[124:125], v[96:97], v[128:129], v[124:125] op_sel:[0,1,0]
	v_pk_fma_f32 v[4:5], v[4:5], v[88:89], v[116:117]
	v_pk_fma_f32 v[12:13], v[12:13], v[88:89], v[124:125]
	v_pk_fma_f32 v[118:119], v[98:99], v[128:129], v[118:119] op_sel_hi:[1,0,1]
	v_pk_fma_f32 v[126:127], v[98:99], v[128:129], v[126:127] op_sel:[0,1,0]
	v_pk_fma_f32 v[6:7], v[6:7], v[90:91], v[118:119]
	v_pk_fma_f32 v[14:15], v[14:15], v[90:91], v[126:127]
	ds_read_b128 v[92:95], v138 offset:16128
	ds_read_b128 v[96:99], v138 offset:16144
	ds_read_b128 v[84:87], v138 offset:15616
	ds_read_b128 v[88:91], v138 offset:15632
	s_waitcnt lgkmcnt(9)
	v_pk_mul_f32 v[128:129], v[8:9], v[68:69]
	v_pk_mul_f32 v[132:133], v[8:9], v[76:77]
	v_pk_mul_f32 v[130:131], v[16:17], v[68:69]
	v_pk_mul_f32 v[134:135], v[16:17], v[76:77]
	v_pk_fma_f32 v[128:129], v[10:11], v[70:71], v[128:129]
	v_pk_fma_f32 v[132:133], v[10:11], v[78:79], v[132:133]
	v_pk_fma_f32 v[130:131], v[18:19], v[70:71], v[130:131]
	v_pk_fma_f32 v[134:135], v[18:19], v[78:79], v[134:135]
	v_pk_fma_f32 v[128:129], v[4:5], v[72:73], v[128:129]
	v_pk_fma_f32 v[132:133], v[4:5], v[80:81], v[132:133]
	v_pk_fma_f32 v[130:131], v[12:13], v[72:73], v[130:131]
	v_pk_fma_f32 v[134:135], v[12:13], v[80:81], v[134:135]
	v_pk_fma_f32 v[128:129], v[6:7], v[74:75], v[128:129]
	v_pk_fma_f32 v[132:133], v[6:7], v[82:83], v[132:133]
	v_pk_fma_f32 v[130:131], v[14:15], v[74:75], v[130:131]
	v_pk_fma_f32 v[134:135], v[14:15], v[82:83], v[134:135]
	ds_read_b128 v[68:71], v138 offset:16896
	ds_read_b128 v[72:75], v138 offset:16912
	ds_read_b128 v[76:79], v138 offset:17408
	ds_read_b128 v[80:83], v138 offset:17424
	s_waitcnt lgkmcnt(10)
	v_pk_mul_f32 v[112:113], v[108:109], v[100:101] op_sel_hi:[0,1]
	v_pk_mul_f32 v[120:121], v[108:109], v[100:101] op_sel:[1,0]
	v_add_f32_e32 v128, v128, v129
	v_add_f32_e32 v132, v132, v133
	v_add_f32_e32 v129, v130, v131
	v_add_f32_e32 v133, v134, v135
	v_pk_mul_f32 v[114:115], v[108:109], v[102:103] op_sel_hi:[0,1]
	v_pk_mul_f32 v[122:123], v[108:109], v[102:103] op_sel:[1,0]
	v_add_f32_dpp v128, v128, v128 quad_perm:[1,0,3,2] row_mask:0xf bank_mask:0xf bound_ctrl:1
	v_add_f32_dpp v132, v132, v132 quad_perm:[1,0,3,2] row_mask:0xf bank_mask:0xf bound_ctrl:1
	v_add_f32_dpp v129, v129, v129 quad_perm:[1,0,3,2] row_mask:0xf bank_mask:0xf bound_ctrl:1
	v_add_f32_dpp v133, v133, v133 quad_perm:[1,0,3,2] row_mask:0xf bank_mask:0xf bound_ctrl:1
	v_pk_mul_f32 v[116:117], v[108:109], v[104:105] op_sel_hi:[0,1]
	v_pk_mul_f32 v[124:125], v[108:109], v[104:105] op_sel:[1,0]
	v_add_f32_dpp v128, v128, v128 quad_perm:[2,3,0,1] row_mask:0xf bank_mask:0xf bound_ctrl:1
	v_add_f32_dpp v132, v132, v132 quad_perm:[2,3,0,1] row_mask:0xf bank_mask:0xf bound_ctrl:1
	v_add_f32_dpp v129, v129, v129 quad_perm:[2,3,0,1] row_mask:0xf bank_mask:0xf bound_ctrl:1
	v_add_f32_dpp v133, v133, v133 quad_perm:[2,3,0,1] row_mask:0xf bank_mask:0xf bound_ctrl:1
	v_pk_mul_f32 v[118:119], v[108:109], v[106:107] op_sel_hi:[0,1]
	v_pk_mul_f32 v[126:127], v[108:109], v[106:107] op_sel:[1,0]
	v_add_f32_dpp v128, v128, v128 row_half_mirror row_mask:0xf bank_mask:0xf bound_ctrl:1
	v_add_f32_dpp v132, v132, v132 row_half_mirror row_mask:0xf bank_mask:0xf bound_ctrl:1
	v_add_f32_dpp v129, v129, v129 row_half_mirror row_mask:0xf bank_mask:0xf bound_ctrl:1
	v_add_f32_dpp v133, v133, v133 row_half_mirror row_mask:0xf bank_mask:0xf bound_ctrl:1
	ds_read_b128 v[100:103], v138 offset:17920
	ds_read_b128 v[104:107], v138 offset:17936
	s_waitcnt lgkmcnt(11)
; __device__ __forceinline__ void rw_load(RwRegs& R, const float* vb, const float* sb, int t, int k0, int vrow0) {
;   const float* vt = vb + t * 384 + k0;
; #pragma unroll
;   for (int q = 0; q < 2; ++q) {
;     R.a[q] = *(const f32x4*)(vt + q * 4);
;     R.wr[q] = *(const f32x4*)(vt + 128 + q * 4);
;     R.w[q] = *(const f32x4*)(vt + 64 + q * 4);
;     R.b[q] = *(const f32x4*)(vt + 192 + q * 4);
;     R.k[q] = *(const f32x4*)(vt + 256 + q * 4);
;   }
;   R.v = *(const f32x2*)(vb + t * 384 + 320 + vrow0);
;   R.sc = *(const f32x4*)(sb + t * 4);
; }
; __device__ __forceinline__ f32x2 rw_step(f32x2 (&S)[2][4], const RwRegs& R) {
;   float sa[2], sy[2];
; #pragma unroll
;   for (int r = 0; r < 2; ++r) {
;     f32x2 a0 = S[r][0] * lo2(R.a[0]);
;     f32x2 a1 = S[r][1] * hi2(R.a[0]);
;     f32x2 y0 = S[r][0] * lo2(R.wr[0]);
;     f32x2 y1 = S[r][1] * hi2(R.wr[0]);
;     a0 += S[r][2] * lo2(R.a[1]);
;     a1 += S[r][3] * hi2(R.a[1]);
;     y0 += S[r][2] * lo2(R.wr[1]);
;     y1 += S[r][3] * hi2(R.wr[1]);
;     a0 += a1; y0 += y1;
;     sa[r] = a0.x + a0.y; sy[r] = y0.x + y0.y;
;   }
;   sa[0] = red8(sa[0]); sa[1] = red8(sa[1]); sy[0] = red8(sy[0]); sy[1] = red8(sy[1]);
;   f32x2 yv;
; #pragma unroll
;   for (int r = 0; r < 2; ++r) {
;     const float vr = r ? R.v.y : R.v.x;
;     const f32x2 sa2 = splat2(sa[r]), vv2 = splat2(vr);
;     S[r][0] = S[r][0] * lo2(R.w[0]) + (sa2 * lo2(R.b[0]) + vv2 * lo2(R.k[0]));
;     S[r][1] = S[r][1] * hi2(R.w[0]) + (sa2 * hi2(R.b[0]) + vv2 * hi2(R.k[0]));
;     S[r][2] = S[r][2] * lo2(R.w[1]) + (sa2 * lo2(R.b[1]) + vv2 * lo2(R.k[1]));
;     S[r][3] = S[r][3] * hi2(R.w[1]) + (sa2 * hi2(R.b[1]) + vv2 * hi2(R.k[1]));
;     const float y = sy[r] + sa[r] * R.sc.x + vr * R.sc.y;
;     if (r) yv.y = y; else yv.x = y;
;   }
;   return yv;
; }
; __device__ __forceinline__ void scan_rwkv(const Params& p, int l, int seq, int h, char* smem, const unsigned* wflags, unsigned wexpect) {
;     ...
;     for (int t = 0; t < nsteps; t += 2) {
;       rw_load(RB, vb, sb, min(t + 1, 15), k0, vrow0);
;       const f32x2 y0v = rw_step(S, RA);
;       *(f32x2*)((part == 0) ? (yb + t * 64 + vrow0) : ydummy) = y0v;
;       SCAN_INTERLEAVE(13, 4);
;       if (t + 1 < nsteps) {
;         rw_load(RA, vb, sb, min(t + 2, 15), k0, vrow0);
;         const f32x2 y1v = rw_step(S, RB);
;         *(f32x2*)((part == 0) ? (yb + (t + 1) * 64 + vrow0) : ydummy) = y1v;
	v_pk_fma_f32 v[136:137], v[128:129], v[110:111], v[132:133] op_sel_hi:[1,0,1]
	s_waitcnt lgkmcnt(8)
	v_pk_fma_f32 v[112:113], v[92:93], v[128:129], v[112:113] op_sel_hi:[1,0,1]
	v_pk_fma_f32 v[136:137], v[108:109], v[110:111], v[136:137] op_sel:[0,1,0]
	v_pk_fma_f32 v[120:121], v[92:93], v[128:129], v[120:121] op_sel:[0,1,0]
	ds_read_b64 v[108:109], v139 offset:18176
	ds_read_b64 v[110:111], v140 offset:49328
	s_waitcnt lgkmcnt(8)
	v_pk_fma_f32 v[8:9], v[8:9], v[84:85], v[112:113]
	ds_write_b64 v141, v[136:137] offset:2560
	v_pk_fma_f32 v[16:17], v[16:17], v[84:85], v[120:121]
	v_pk_fma_f32 v[114:115], v[94:95], v[128:129], v[114:115] op_sel_hi:[1,0,1]
	v_pk_fma_f32 v[122:123], v[94:95], v[128:129], v[122:123] op_sel:[0,1,0]
	v_pk_fma_f32 v[10:11], v[10:11], v[86:87], v[114:115]
	v_pk_fma_f32 v[18:19], v[18:19], v[86:87], v[122:123]
	v_pk_fma_f32 v[116:117], v[96:97], v[128:129], v[116:117] op_sel_hi:[1,0,1]
	v_pk_fma_f32 v[124:125], v[96:97], v[128:129], v[124:125] op_sel:[0,1,0]
	v_pk_fma_f32 v[4:5], v[4:5], v[88:89], v[116:117]
	v_pk_fma_f32 v[12:13], v[12:13], v[88:89], v[124:125]
	v_pk_fma_f32 v[118:119], v[98:99], v[128:129], v[118:119] op_sel_hi:[1,0,1]
	v_pk_fma_f32 v[126:127], v[98:99], v[128:129], v[126:127] op_sel:[0,1,0]
	v_pk_fma_f32 v[6:7], v[6:7], v[90:91], v[118:119]
	v_pk_fma_f32 v[14:15], v[14:15], v[90:91], v[126:127]
	ds_read_b128 v[92:95], v138 offset:17664
	ds_read_b128 v[96:99], v138 offset:17680
	ds_read_b128 v[84:87], v138 offset:17152
	ds_read_b128 v[88:91], v138 offset:17168
	s_waitcnt lgkmcnt(9)
	v_pk_mul_f32 v[128:129], v[8:9], v[68:69]
	v_pk_mul_f32 v[132:133], v[8:9], v[76:77]
	v_pk_mul_f32 v[130:131], v[16:17], v[68:69]
	v_pk_mul_f32 v[134:135], v[16:17], v[76:77]
	v_pk_fma_f32 v[128:129], v[10:11], v[70:71], v[128:129]
	v_pk_fma_f32 v[132:133], v[10:11], v[78:79], v[132:133]
	v_pk_fma_f32 v[130:131], v[18:19], v[70:71], v[130:131]
	v_pk_fma_f32 v[134:135], v[18:19], v[78:79], v[134:135]
	v_pk_fma_f32 v[128:129], v[4:5], v[72:73], v[128:129]
	v_pk_fma_f32 v[132:133], v[4:5], v[80:81], v[132:133]
	v_pk_fma_f32 v[130:131], v[12:13], v[72:73], v[130:131]
	v_pk_fma_f32 v[134:135], v[12:13], v[80:81], v[134:135]
	v_pk_fma_f32 v[128:129], v[6:7], v[74:75], v[128:129]
	v_pk_fma_f32 v[132:133], v[6:7], v[82:83], v[132:133]
	v_pk_fma_f32 v[130:131], v[14:15], v[74:75], v[130:131]
	v_pk_fma_f32 v[134:135], v[14:15], v[82:83], v[134:135]
	ds_read_b128 v[68:71], v138 offset:18432
	ds_read_b128 v[72:75], v138 offset:18448
	ds_read_b128 v[76:79], v138 offset:18944
	ds_read_b128 v[80:83], v138 offset:18960
	s_waitcnt lgkmcnt(10)
	v_pk_mul_f32 v[112:113], v[108:109], v[100:101] op_sel_hi:[0,1]
	v_pk_mul_f32 v[120:121], v[108:109], v[100:101] op_sel:[1,0]
	v_add_f32_e32 v128, v128, v129
	v_add_f32_e32 v132, v132, v133
	v_add_f32_e32 v129, v130, v131
	v_add_f32_e32 v133, v134, v135
	v_pk_mul_f32 v[114:115], v[108:109], v[102:103] op_sel_hi:[0,1]
	v_pk_mul_f32 v[122:123], v[108:109], v[102:103] op_sel:[1,0]
	v_add_f32_dpp v128, v128, v128 quad_perm:[1,0,3,2] row_mask:0xf bank_mask:0xf bound_ctrl:1
	v_add_f32_dpp v132, v132, v132 quad_perm:[1,0,3,2] row_mask:0xf bank_mask:0xf bound_ctrl:1
	v_add_f32_dpp v129, v129, v129 quad_perm:[1,0,3,2] row_mask:0xf bank_mask:0xf bound_ctrl:1
	v_add_f32_dpp v133, v133, v133 quad_perm:[1,0,3,2] row_mask:0xf bank_mask:0xf bound_ctrl:1
	v_pk_mul_f32 v[116:117], v[108:109], v[104:105] op_sel_hi:[0,1]
	v_pk_mul_f32 v[124:125], v[108:109], v[104:105] op_sel:[1,0]
	v_add_f32_dpp v128, v128, v128 quad_perm:[2,3,0,1] row_mask:0xf bank_mask:0xf bound_ctrl:1
	v_add_f32_dpp v132, v132, v132 quad_perm:[2,3,0,1] row_mask:0xf bank_mask:0xf bound_ctrl:1
	v_add_f32_dpp v129, v129, v129 quad_perm:[2,3,0,1] row_mask:0xf bank_mask:0xf bound_ctrl:1
	v_add_f32_dpp v133, v133, v133 quad_perm:[2,3,0,1] row_mask:0xf bank_mask:0xf bound_ctrl:1
	v_pk_mul_f32 v[118:119], v[108:109], v[106:107] op_sel_hi:[0,1]
	v_pk_mul_f32 v[126:127], v[108:109], v[106:107] op_sel:[1,0]
	v_add_f32_dpp v128, v128, v128 row_half_mirror row_mask:0xf bank_mask:0xf bound_ctrl:1
	v_add_f32_dpp v132, v132, v132 row_half_mirror row_mask:0xf bank_mask:0xf bound_ctrl:1
	v_add_f32_dpp v129, v129, v129 row_half_mirror row_mask:0xf bank_mask:0xf bound_ctrl:1
	v_add_f32_dpp v133, v133, v133 row_half_mirror row_mask:0xf bank_mask:0xf bound_ctrl:1
	ds_read_b128 v[100:103], v138 offset:19456
	ds_read_b128 v[104:107], v138 offset:19472
	s_waitcnt lgkmcnt(11)
	v_pk_fma_f32 v[136:137], v[128:129], v[110:111], v[132:133] op_sel_hi:[1,0,1]
	s_waitcnt lgkmcnt(8)
	v_pk_fma_f32 v[112:113], v[92:93], v[128:129], v[112:113] op_sel_hi:[1,0,1]
	v_pk_fma_f32 v[136:137], v[108:109], v[110:111], v[136:137] op_sel:[0,1,0]
	v_pk_fma_f32 v[120:121], v[92:93], v[128:129], v[120:121] op_sel:[0,1,0]
	ds_read_b64 v[108:109], v139 offset:19712
	ds_read_b64 v[110:111], v140 offset:49344
	s_waitcnt lgkmcnt(8)
	v_pk_fma_f32 v[8:9], v[8:9], v[84:85], v[112:113]
	ds_write_b64 v141, v[136:137] offset:2816
	v_pk_fma_f32 v[16:17], v[16:17], v[84:85], v[120:121]
	v_pk_fma_f32 v[114:115], v[94:95], v[128:129], v[114:115] op_sel_hi:[1,0,1]
	v_pk_fma_f32 v[122:123], v[94:95], v[128:129], v[122:123] op_sel:[0,1,0]
	v_pk_fma_f32 v[10:11], v[10:11], v[86:87], v[114:115]
	v_pk_fma_f32 v[18:19], v[18:19], v[86:87], v[122:123]
	v_pk_fma_f32 v[116:117], v[96:97], v[128:129], v[116:117] op_sel_hi:[1,0,1]
	v_pk_fma_f32 v[124:125], v[96:97], v[128:129], v[124:125] op_sel:[0,1,0]
	v_pk_fma_f32 v[4:5], v[4:5], v[88:89], v[116:117]
	v_pk_fma_f32 v[12:13], v[12:13], v[88:89], v[124:125]
	v_pk_fma_f32 v[118:119], v[98:99], v[128:129], v[118:119] op_sel_hi:[1,0,1]
	v_pk_fma_f32 v[126:127], v[98:99], v[128:129], v[126:127] op_sel:[0,1,0]
	v_pk_fma_f32 v[6:7], v[6:7], v[90:91], v[118:119]
	v_pk_fma_f32 v[14:15], v[14:15], v[90:91], v[126:127]
	ds_read_b128 v[92:95], v138 offset:19200
	ds_read_b128 v[96:99], v138 offset:19216
	ds_read_b128 v[84:87], v138 offset:18688
	ds_read_b128 v[88:91], v138 offset:18704
	s_waitcnt lgkmcnt(9)
; __device__ __forceinline__ void rw_load(RwRegs& R, const float* vb, const float* sb, int t, int k0, int vrow0) {
;   const float* vt = vb + t * 384 + k0;
; #pragma unroll
;   for (int q = 0; q < 2; ++q) {
;     R.a[q] = *(const f32x4*)(vt + q * 4);
;     R.wr[q] = *(const f32x4*)(vt + 128 + q * 4);
;     R.w[q] = *(const f32x4*)(vt + 64 + q * 4);
;     R.b[q] = *(const f32x4*)(vt + 192 + q * 4);
;     R.k[q] = *(const f32x4*)(vt + 256 + q * 4);
;   }
;   R.v = *(const f32x2*)(vb + t * 384 + 320 + vrow0);
;   R.sc = *(const f32x4*)(sb + t * 4);
; }
; __device__ __forceinline__ f32x2 rw_step(f32x2 (&S)[2][4], const RwRegs& R) {
;   float sa[2], sy[2];
; #pragma unroll
;   for (int r = 0; r < 2; ++r) {
;     f32x2 a0 = S[r][0] * lo2(R.a[0]);
;     f32x2 a1 = S[r][1] * hi2(R.a[0]);
;     f32x2 y0 = S[r][0] * lo2(R.wr[0]);
;     f32x2 y1 = S[r][1] * hi2(R.wr[0]);
;     a0 += S[r][2] * lo2(R.a[1]);
;     a1 += S[r][3] * hi2(R.a[1]);
;     y0 += S[r][2] * lo2(R.wr[1]);
;     y1 += S[r][3] * hi2(R.wr[1]);
;     a0 += a1; y0 += y1;
;     sa[r] = a0.x + a0.y; sy[r] = y0.x + y0.y;
;   }
;   sa[0] = red8(sa[0]); sa[1] = red8(sa[1]); sy[0] = red8(sy[0]); sy[1] = red8(sy[1]);
;   f32x2 yv;
; #pragma unroll
;   for (int r = 0; r < 2; ++r) {
;     const float vr = r ? R.v.y : R.v.x;
;     const f32x2 sa2 = splat2(sa[r]), vv2 = splat2(vr);
;     S[r][0] = S[r][0] * lo2(R.w[0]) + (sa2 * lo2(R.b[0]) + vv2 * lo2(R.k[0]));
;     S[r][1] = S[r][1] * hi2(R.w[0]) + (sa2 * hi2(R.b[0]) + vv2 * hi2(R.k[0]));
;     S[r][2] = S[r][2] * lo2(R.w[1]) + (sa2 * lo2(R.b[1]) + vv2 * lo2(R.k[1]));
;     S[r][3] = S[r][3] * hi2(R.w[1]) + (sa2 * hi2(R.b[1]) + vv2 * hi2(R.k[1]));
;     const float y = sy[r] + sa[r] * R.sc.x + vr * R.sc.y;
;     if (r) yv.y = y; else yv.x = y;
;   }
;   return yv;
; }
; __device__ __forceinline__ void scan_rwkv(const Params& p, int l, int seq, int h, char* smem, const unsigned* wflags, unsigned wexpect) {
;     ...
;     for (int t = 0; t < nsteps; t += 2) {
;       rw_load(RB, vb, sb, min(t + 1, 15), k0, vrow0);
;       const f32x2 y0v = rw_step(S, RA);
;       *(f32x2*)((part == 0) ? (yb + t * 64 + vrow0) : ydummy) = y0v;
;       SCAN_INTERLEAVE(13, 4);
;       if (t + 1 < nsteps) {
;         rw_load(RA, vb, sb, min(t + 2, 15), k0, vrow0);
;         const f32x2 y1v = rw_step(S, RB);
;         *(f32x2*)((part == 0) ? (yb + (t + 1) * 64 + vrow0) : ydummy) = y1v;
	v_pk_mul_f32 v[128:129], v[8:9], v[68:69]
	v_pk_mul_f32 v[132:133], v[8:9], v[76:77]
	v_pk_mul_f32 v[130:131], v[16:17], v[68:69]
	v_pk_mul_f32 v[134:135], v[16:17], v[76:77]
	v_pk_fma_f32 v[128:129], v[10:11], v[70:71], v[128:129]
	v_pk_fma_f32 v[132:133], v[10:11], v[78:79], v[132:133]
	v_pk_fma_f32 v[130:131], v[18:19], v[70:71], v[130:131]
	v_pk_fma_f32 v[134:135], v[18:19], v[78:79], v[134:135]
	v_pk_fma_f32 v[128:129], v[4:5], v[72:73], v[128:129]
	v_pk_fma_f32 v[132:133], v[4:5], v[80:81], v[132:133]
	v_pk_fma_f32 v[130:131], v[12:13], v[72:73], v[130:131]
	v_pk_fma_f32 v[134:135], v[12:13], v[80:81], v[134:135]
	v_pk_fma_f32 v[128:129], v[6:7], v[74:75], v[128:129]
	v_pk_fma_f32 v[132:133], v[6:7], v[82:83], v[132:133]
	v_pk_fma_f32 v[130:131], v[14:15], v[74:75], v[130:131]
	v_pk_fma_f32 v[134:135], v[14:15], v[82:83], v[134:135]
	ds_read_b128 v[68:71], v138 offset:19968
	ds_read_b128 v[72:75], v138 offset:19984
	ds_read_b128 v[76:79], v138 offset:20480
	ds_read_b128 v[80:83], v138 offset:20496
	s_waitcnt lgkmcnt(10)
	v_pk_mul_f32 v[112:113], v[108:109], v[100:101] op_sel_hi:[0,1]
	v_pk_mul_f32 v[120:121], v[108:109], v[100:101] op_sel:[1,0]
	v_add_f32_e32 v128, v128, v129
	v_add_f32_e32 v132, v132, v133
	v_add_f32_e32 v129, v130, v131
	v_add_f32_e32 v133, v134, v135
	v_pk_mul_f32 v[114:115], v[108:109], v[102:103] op_sel_hi:[0,1]
	v_pk_mul_f32 v[122:123], v[108:109], v[102:103] op_sel:[1,0]
	v_add_f32_dpp v128, v128, v128 quad_perm:[1,0,3,2] row_mask:0xf bank_mask:0xf bound_ctrl:1
	v_add_f32_dpp v132, v132, v132 quad_perm:[1,0,3,2] row_mask:0xf bank_mask:0xf bound_ctrl:1
	v_add_f32_dpp v129, v129, v129 quad_perm:[1,0,3,2] row_mask:0xf bank_mask:0xf bound_ctrl:1
	v_add_f32_dpp v133, v133, v133 quad_perm:[1,0,3,2] row_mask:0xf bank_mask:0xf bound_ctrl:1
	v_pk_mul_f32 v[116:117], v[108:109], v[104:105] op_sel_hi:[0,1]
	v_pk_mul_f32 v[124:125], v[108:109], v[104:105] op_sel:[1,0]
	v_add_f32_dpp v128, v128, v128 quad_perm:[2,3,0,1] row_mask:0xf bank_mask:0xf bound_ctrl:1
	v_add_f32_dpp v132, v132, v132 quad_perm:[2,3,0,1] row_mask:0xf bank_mask:0xf bound_ctrl:1
	v_add_f32_dpp v129, v129, v129 quad_perm:[2,3,0,1] row_mask:0xf bank_mask:0xf bound_ctrl:1
	v_add_f32_dpp v133, v133, v133 quad_perm:[2,3,0,1] row_mask:0xf bank_mask:0xf bound_ctrl:1
	v_pk_mul_f32 v[118:119], v[108:109], v[106:107] op_sel_hi:[0,1]
	v_pk_mul_f32 v[126:127], v[108:109], v[106:107] op_sel:[1,0]
	v_add_f32_dpp v128, v128, v128 row_half_mirror row_mask:0xf bank_mask:0xf bound_ctrl:1
	v_add_f32_dpp v132, v132, v132 row_half_mirror row_mask:0xf bank_mask:0xf bound_ctrl:1
	v_add_f32_dpp v129, v129, v129 row_half_mirror row_mask:0xf bank_mask:0xf bound_ctrl:1
	v_add_f32_dpp v133, v133, v133 row_half_mirror row_mask:0xf bank_mask:0xf bound_ctrl:1
	ds_read_b128 v[100:103], v138 offset:20992
	ds_read_b128 v[104:107], v138 offset:21008
	s_waitcnt lgkmcnt(11)
	v_pk_fma_f32 v[136:137], v[128:129], v[110:111], v[132:133] op_sel_hi:[1,0,1]
	s_waitcnt lgkmcnt(8)
	v_pk_fma_f32 v[112:113], v[92:93], v[128:129], v[112:113] op_sel_hi:[1,0,1]
	v_pk_fma_f32 v[136:137], v[108:109], v[110:111], v[136:137] op_sel:[0,1,0]
	v_pk_fma_f32 v[120:121], v[92:93], v[128:129], v[120:121] op_sel:[0,1,0]
	ds_read_b64 v[108:109], v139 offset:21248
	ds_read_b64 v[110:111], v140 offset:49360
	s_waitcnt lgkmcnt(8)
	v_pk_fma_f32 v[8:9], v[8:9], v[84:85], v[112:113]
	ds_write_b64 v141, v[136:137] offset:3072
	v_pk_fma_f32 v[16:17], v[16:17], v[84:85], v[120:121]
	v_pk_fma_f32 v[114:115], v[94:95], v[128:129], v[114:115] op_sel_hi:[1,0,1]
	v_pk_fma_f32 v[122:123], v[94:95], v[128:129], v[122:123] op_sel:[0,1,0]
	v_pk_fma_f32 v[10:11], v[10:11], v[86:87], v[114:115]
	v_pk_fma_f32 v[18:19], v[18:19], v[86:87], v[122:123]
	v_pk_fma_f32 v[116:117], v[96:97], v[128:129], v[116:117] op_sel_hi:[1,0,1]
	v_pk_fma_f32 v[124:125], v[96:97], v[128:129], v[124:125] op_sel:[0,1,0]
	v_pk_fma_f32 v[4:5], v[4:5], v[88:89], v[116:117]
	v_pk_fma_f32 v[12:13], v[12:13], v[88:89], v[124:125]
	v_pk_fma_f32 v[118:119], v[98:99], v[128:129], v[118:119] op_sel_hi:[1,0,1]
	v_pk_fma_f32 v[126:127], v[98:99], v[128:129], v[126:127] op_sel:[0,1,0]
	v_pk_fma_f32 v[6:7], v[6:7], v[90:91], v[118:119]
	v_pk_fma_f32 v[14:15], v[14:15], v[90:91], v[126:127]
	ds_read_b128 v[92:95], v138 offset:20736
	ds_read_b128 v[96:99], v138 offset:20752
	ds_read_b128 v[84:87], v138 offset:20224
	ds_read_b128 v[88:91], v138 offset:20240
	s_waitcnt lgkmcnt(9)
	v_pk_mul_f32 v[128:129], v[8:9], v[68:69]
	v_pk_mul_f32 v[132:133], v[8:9], v[76:77]
	v_pk_mul_f32 v[130:131], v[16:17], v[68:69]
	v_pk_mul_f32 v[134:135], v[16:17], v[76:77]
	v_pk_fma_f32 v[128:129], v[10:11], v[70:71], v[128:129]
	v_pk_fma_f32 v[132:133], v[10:11], v[78:79], v[132:133]
	v_pk_fma_f32 v[130:131], v[18:19], v[70:71], v[130:131]
	v_pk_fma_f32 v[134:135], v[18:19], v[78:79], v[134:135]
	v_pk_fma_f32 v[128:129], v[4:5], v[72:73], v[128:129]
	v_pk_fma_f32 v[132:133], v[4:5], v[80:81], v[132:133]
	v_pk_fma_f32 v[130:131], v[12:13], v[72:73], v[130:131]
	v_pk_fma_f32 v[134:135], v[12:13], v[80:81], v[134:135]
	v_pk_fma_f32 v[128:129], v[6:7], v[74:75], v[128:129]
	v_pk_fma_f32 v[132:133], v[6:7], v[82:83], v[132:133]
	v_pk_fma_f32 v[130:131], v[14:15], v[74:75], v[130:131]
	v_pk_fma_f32 v[134:135], v[14:15], v[82:83], v[134:135]
	ds_read_b128 v[68:71], v138 offset:21504
	ds_read_b128 v[72:75], v138 offset:21520
	ds_read_b128 v[76:79], v138 offset:22016
	ds_read_b128 v[80:83], v138 offset:22032
	s_waitcnt lgkmcnt(10)
; __device__ __forceinline__ void rw_load(RwRegs& R, const float* vb, const float* sb, int t, int k0, int vrow0) {
;   const float* vt = vb + t * 384 + k0;
; #pragma unroll
;   for (int q = 0; q < 2; ++q) {
;     R.a[q] = *(const f32x4*)(vt + q * 4);
;     R.wr[q] = *(const f32x4*)(vt + 128 + q * 4);
;     R.w[q] = *(const f32x4*)(vt + 64 + q * 4);
;     R.b[q] = *(const f32x4*)(vt + 192 + q * 4);
;     R.k[q] = *(const f32x4*)(vt + 256 + q * 4);
;   }
;   R.v = *(const f32x2*)(vb + t * 384 + 320 + vrow0);
;   R.sc = *(const f32x4*)(sb + t * 4);
; }
; __device__ __forceinline__ f32x2 rw_step(f32x2 (&S)[2][4], const RwRegs& R) {
;   float sa[2], sy[2];
; #pragma unroll
;   for (int r = 0; r < 2; ++r) {
;     f32x2 a0 = S[r][0] * lo2(R.a[0]);
;     f32x2 a1 = S[r][1] * hi2(R.a[0]);
;     f32x2 y0 = S[r][0] * lo2(R.wr[0]);
;     f32x2 y1 = S[r][1] * hi2(R.wr[0]);
;     a0 += S[r][2] * lo2(R.a[1]);
;     a1 += S[r][3] * hi2(R.a[1]);
;     y0 += S[r][2] * lo2(R.wr[1]);
;     y1 += S[r][3] * hi2(R.wr[1]);
;     a0 += a1; y0 += y1;
;     sa[r] = a0.x + a0.y; sy[r] = y0.x + y0.y;
;   }
;   sa[0] = red8(sa[0]); sa[1] = red8(sa[1]); sy[0] = red8(sy[0]); sy[1] = red8(sy[1]);
;   f32x2 yv;
; #pragma unroll
;   for (int r = 0; r < 2; ++r) {
;     const float vr = r ? R.v.y : R.v.x;
;     const f32x2 sa2 = splat2(sa[r]), vv2 = splat2(vr);
;     S[r][0] = S[r][0] * lo2(R.w[0]) + (sa2 * lo2(R.b[0]) + vv2 * lo2(R.k[0]));
;     S[r][1] = S[r][1] * hi2(R.w[0]) + (sa2 * hi2(R.b[0]) + vv2 * hi2(R.k[0]));
;     S[r][2] = S[r][2] * lo2(R.w[1]) + (sa2 * lo2(R.b[1]) + vv2 * lo2(R.k[1]));
;     S[r][3] = S[r][3] * hi2(R.w[1]) + (sa2 * hi2(R.b[1]) + vv2 * hi2(R.k[1]));
;     const float y = sy[r] + sa[r] * R.sc.x + vr * R.sc.y;
;     if (r) yv.y = y; else yv.x = y;
;   }
;   return yv;
; }
; __device__ __forceinline__ void scan_rwkv(const Params& p, int l, int seq, int h, char* smem, const unsigned* wflags, unsigned wexpect) {
;     ...
;     for (int t = 0; t < nsteps; t += 2) {
;       rw_load(RB, vb, sb, min(t + 1, 15), k0, vrow0);
;       const f32x2 y0v = rw_step(S, RA);
;       *(f32x2*)((part == 0) ? (yb + t * 64 + vrow0) : ydummy) = y0v;
;       SCAN_INTERLEAVE(13, 4);
;       if (t + 1 < nsteps) {
;         rw_load(RA, vb, sb, min(t + 2, 15), k0, vrow0);
;         const f32x2 y1v = rw_step(S, RB);
;         *(f32x2*)((part == 0) ? (yb + (t + 1) * 64 + vrow0) : ydummy) = y1v;
	v_pk_mul_f32 v[112:113], v[108:109], v[100:101] op_sel_hi:[0,1]
	v_pk_mul_f32 v[120:121], v[108:109], v[100:101] op_sel:[1,0]
	v_add_f32_e32 v128, v128, v129
	v_add_f32_e32 v132, v132, v133
	v_add_f32_e32 v129, v130, v131
	v_add_f32_e32 v133, v134, v135
	v_pk_mul_f32 v[114:115], v[108:109], v[102:103] op_sel_hi:[0,1]
	v_pk_mul_f32 v[122:123], v[108:109], v[102:103] op_sel:[1,0]
	v_add_f32_dpp v128, v128, v128 quad_perm:[1,0,3,2] row_mask:0xf bank_mask:0xf bound_ctrl:1
	v_add_f32_dpp v132, v132, v132 quad_perm:[1,0,3,2] row_mask:0xf bank_mask:0xf bound_ctrl:1
	v_add_f32_dpp v129, v129, v129 quad_perm:[1,0,3,2] row_mask:0xf bank_mask:0xf bound_ctrl:1
	v_add_f32_dpp v133, v133, v133 quad_perm:[1,0,3,2] row_mask:0xf bank_mask:0xf bound_ctrl:1
	v_pk_mul_f32 v[116:117], v[108:109], v[104:105] op_sel_hi:[0,1]
	v_pk_mul_f32 v[124:125], v[108:109], v[104:105] op_sel:[1,0]
	v_add_f32_dpp v128, v128, v128 quad_perm:[2,3,0,1] row_mask:0xf bank_mask:0xf bound_ctrl:1
	v_add_f32_dpp v132, v132, v132 quad_perm:[2,3,0,1] row_mask:0xf bank_mask:0xf bound_ctrl:1
	v_add_f32_dpp v129, v129, v129 quad_perm:[2,3,0,1] row_mask:0xf bank_mask:0xf bound_ctrl:1
	v_add_f32_dpp v133, v133, v133 quad_perm:[2,3,0,1] row_mask:0xf bank_mask:0xf bound_ctrl:1
	v_pk_mul_f32 v[118:119], v[108:109], v[106:107] op_sel_hi:[0,1]
	v_pk_mul_f32 v[126:127], v[108:109], v[106:107] op_sel:[1,0]
	v_add_f32_dpp v128, v128, v128 row_half_mirror row_mask:0xf bank_mask:0xf bound_ctrl:1
	v_add_f32_dpp v132, v132, v132 row_half_mirror row_mask:0xf bank_mask:0xf bound_ctrl:1
	v_add_f32_dpp v129, v129, v129 row_half_mirror row_mask:0xf bank_mask:0xf bound_ctrl:1
	v_add_f32_dpp v133, v133, v133 row_half_mirror row_mask:0xf bank_mask:0xf bound_ctrl:1
	ds_read_b128 v[100:103], v138 offset:22528
	ds_read_b128 v[104:107], v138 offset:22544
	s_waitcnt lgkmcnt(11)
	v_pk_fma_f32 v[136:137], v[128:129], v[110:111], v[132:133] op_sel_hi:[1,0,1]
	s_waitcnt lgkmcnt(8)
	v_pk_fma_f32 v[112:113], v[92:93], v[128:129], v[112:113] op_sel_hi:[1,0,1]
	v_pk_fma_f32 v[136:137], v[108:109], v[110:111], v[136:137] op_sel:[0,1,0]
	v_pk_fma_f32 v[120:121], v[92:93], v[128:129], v[120:121] op_sel:[0,1,0]
	ds_read_b64 v[108:109], v139 offset:22784
	ds_read_b64 v[110:111], v140 offset:49376
	s_waitcnt lgkmcnt(8)
	v_pk_fma_f32 v[8:9], v[8:9], v[84:85], v[112:113]
	ds_write_b64 v141, v[136:137] offset:3328
	v_pk_fma_f32 v[16:17], v[16:17], v[84:85], v[120:121]
	v_pk_fma_f32 v[114:115], v[94:95], v[128:129], v[114:115] op_sel_hi:[1,0,1]
	v_pk_fma_f32 v[122:123], v[94:95], v[128:129], v[122:123] op_sel:[0,1,0]
	v_pk_fma_f32 v[10:11], v[10:11], v[86:87], v[114:115]
	v_pk_fma_f32 v[18:19], v[18:19], v[86:87], v[122:123]
	v_pk_fma_f32 v[116:117], v[96:97], v[128:129], v[116:117] op_sel_hi:[1,0,1]
	v_pk_fma_f32 v[124:125], v[96:97], v[128:129], v[124:125] op_sel:[0,1,0]
	v_pk_fma_f32 v[4:5], v[4:5], v[88:89], v[116:117]
	v_pk_fma_f32 v[12:13], v[12:13], v[88:89], v[124:125]
	v_pk_fma_f32 v[118:119], v[98:99], v[128:129], v[118:119] op_sel_hi:[1,0,1]
	v_pk_fma_f32 v[126:127], v[98:99], v[128:129], v[126:127] op_sel:[0,1,0]
	v_pk_fma_f32 v[6:7], v[6:7], v[90:91], v[118:119]
	v_pk_fma_f32 v[14:15], v[14:15], v[90:91], v[126:127]
	ds_read_b128 v[92:95], v138 offset:22272
	ds_read_b128 v[96:99], v138 offset:22288
	ds_read_b128 v[84:87], v138 offset:21760
	ds_read_b128 v[88:91], v138 offset:21776
	s_waitcnt lgkmcnt(9)
	v_pk_mul_f32 v[128:129], v[8:9], v[68:69]
	v_pk_mul_f32 v[132:133], v[8:9], v[76:77]
	v_pk_mul_f32 v[130:131], v[16:17], v[68:69]
	v_pk_mul_f32 v[134:135], v[16:17], v[76:77]
	v_pk_fma_f32 v[128:129], v[10:11], v[70:71], v[128:129]
	v_pk_fma_f32 v[132:133], v[10:11], v[78:79], v[132:133]
	v_pk_fma_f32 v[130:131], v[18:19], v[70:71], v[130:131]
	v_pk_fma_f32 v[134:135], v[18:19], v[78:79], v[134:135]
	v_pk_fma_f32 v[128:129], v[4:5], v[72:73], v[128:129]
	v_pk_fma_f32 v[132:133], v[4:5], v[80:81], v[132:133]
	v_pk_fma_f32 v[130:131], v[12:13], v[72:73], v[130:131]
	v_pk_fma_f32 v[134:135], v[12:13], v[80:81], v[134:135]
	v_pk_fma_f32 v[128:129], v[6:7], v[74:75], v[128:129]
	v_pk_fma_f32 v[132:133], v[6:7], v[82:83], v[132:133]
	v_pk_fma_f32 v[130:131], v[14:15], v[74:75], v[130:131]
	v_pk_fma_f32 v[134:135], v[14:15], v[82:83], v[134:135]
	ds_read_b128 v[68:71], v138 offset:23040
	ds_read_b128 v[72:75], v138 offset:23056
	ds_read_b128 v[76:79], v138 offset:23552
	ds_read_b128 v[80:83], v138 offset:23568
	s_waitcnt lgkmcnt(10)
	v_pk_mul_f32 v[112:113], v[108:109], v[100:101] op_sel_hi:[0,1]
	v_pk_mul_f32 v[120:121], v[108:109], v[100:101] op_sel:[1,0]
	v_add_f32_e32 v128, v128, v129
	v_add_f32_e32 v132, v132, v133
	v_add_f32_e32 v129, v130, v131
	v_add_f32_e32 v133, v134, v135
	v_pk_mul_f32 v[114:115], v[108:109], v[102:103] op_sel_hi:[0,1]
	v_pk_mul_f32 v[122:123], v[108:109], v[102:103] op_sel:[1,0]
	v_add_f32_dpp v128, v128, v128 quad_perm:[1,0,3,2] row_mask:0xf bank_mask:0xf bound_ctrl:1
	v_add_f32_dpp v132, v132, v132 quad_perm:[1,0,3,2] row_mask:0xf bank_mask:0xf bound_ctrl:1
	v_add_f32_dpp v129, v129, v129 quad_perm:[1,0,3,2] row_mask:0xf bank_mask:0xf bound_ctrl:1
	v_add_f32_dpp v133, v133, v133 quad_perm:[1,0,3,2] row_mask:0xf bank_mask:0xf bound_ctrl:1
	v_pk_mul_f32 v[116:117], v[108:109], v[104:105] op_sel_hi:[0,1]
	v_pk_mul_f32 v[124:125], v[108:109], v[104:105] op_sel:[1,0]
	v_add_f32_dpp v128, v128, v128 quad_perm:[2,3,0,1] row_mask:0xf bank_mask:0xf bound_ctrl:1
	v_add_f32_dpp v132, v132, v132 quad_perm:[2,3,0,1] row_mask:0xf bank_mask:0xf bound_ctrl:1
	v_add_f32_dpp v129, v129, v129 quad_perm:[2,3,0,1] row_mask:0xf bank_mask:0xf bound_ctrl:1
	v_add_f32_dpp v133, v133, v133 quad_perm:[2,3,0,1] row_mask:0xf bank_mask:0xf bound_ctrl:1
	v_pk_mul_f32 v[118:119], v[108:109], v[106:107] op_sel_hi:[0,1]
	v_pk_mul_f32 v[126:127], v[108:109], v[106:107] op_sel:[1,0]
	v_add_f32_dpp v128, v128, v128 row_half_mirror row_mask:0xf bank_mask:0xf bound_ctrl:1
	v_add_f32_dpp v132, v132, v132 row_half_mirror row_mask:0xf bank_mask:0xf bound_ctrl:1
	v_add_f32_dpp v129, v129, v129 row_half_mirror row_mask:0xf bank_mask:0xf bound_ctrl:1
	v_add_f32_dpp v133, v133, v133 row_half_mirror row_mask:0xf bank_mask:0xf bound_ctrl:1
	ds_read_b128 v[100:103], v138 offset:24064
	ds_read_b128 v[104:107], v138 offset:24080
	s_waitcnt lgkmcnt(11)
; __device__ __forceinline__ float red8(float v) { v = red4(v); v += dppf<0x141>(v); return v; }
; __device__ __forceinline__ f32x2 lo2(const f32x4& v) { return __builtin_shufflevector(v, v, 0, 1); }
; __device__ __forceinline__ f32x2 hi2(const f32x4& v) { return __builtin_shufflevector(v, v, 2, 3); }
; __device__ __forceinline__ f32x2 splat2(float x) { return (f32x2){x, x}; }
; __device__ __forceinline__ f32x2 rw_step(f32x2 (&S)[2][4], const RwRegs& R) {
;   float sa[2], sy[2];
; #pragma unroll
;   for (int r = 0; r < 2; ++r) {
;     f32x2 a0 = S[r][0] * lo2(R.a[0]);
;     f32x2 a1 = S[r][1] * hi2(R.a[0]);
;     f32x2 y0 = S[r][0] * lo2(R.wr[0]);
;     f32x2 y1 = S[r][1] * hi2(R.wr[0]);
;     a0 += S[r][2] * lo2(R.a[1]);
;     a1 += S[r][3] * hi2(R.a[1]);
;     y0 += S[r][2] * lo2(R.wr[1]);
;     y1 += S[r][3] * hi2(R.wr[1]);
;     a0 += a1; y0 += y1;
;     sa[r] = a0.x + a0.y; sy[r] = y0.x + y0.y;
;   }
;   sa[0] = red8(sa[0]); sa[1] = red8(sa[1]); sy[0] = red8(sy[0]); sy[1] = red8(sy[1]);
;   f32x2 yv;
; #pragma unroll
;   for (int r = 0; r < 2; ++r) {
;     const float vr = r ? R.v.y : R.v.x;
;     const f32x2 sa2 = splat2(sa[r]), vv2 = splat2(vr);
;     S[r][0] = S[r][0] * lo2(R.w[0]) + (sa2 * lo2(R.b[0]) + vv2 * lo2(R.k[0]));
;     S[r][1] = S[r][1] * hi2(R.w[0]) + (sa2 * hi2(R.b[0]) + vv2 * hi2(R.k[0]));
;     S[r][2] = S[r][2] * lo2(R.w[1]) + (sa2 * lo2(R.b[1]) + vv2 * lo2(R.k[1]));
;     S[r][3] = S[r][3] * hi2(R.w[1]) + (sa2 * hi2(R.b[1]) + vv2 * hi2(R.k[1]));
;     const float y = sy[r] + sa[r] * R.sc.x + vr * R.sc.y;
;     if (r) yv.y = y; else yv.x = y;
;   }
;   return yv;
; }
; __device__ __forceinline__ void scan_rwkv(const Params& p, int l, int seq, int h, char* smem, const unsigned* wflags, unsigned wexpect) {
;     ...
;     for (int t = 0; t < nsteps; t += 2) {
;       rw_load(RB, vb, sb, min(t + 1, 15), k0, vrow0);
;       const f32x2 y0v = rw_step(S, RA);
;       *(f32x2*)((part == 0) ? (yb + t * 64 + vrow0) : ydummy) = y0v;
;       SCAN_INTERLEAVE(13, 4);
;       if (t + 1 < nsteps) {
;         rw_load(RA, vb, sb, min(t + 2, 15), k0, vrow0);
;         const f32x2 y1v = rw_step(S, RB);
;         *(f32x2*)((part == 0) ? (yb + (t + 1) * 64 + vrow0) : ydummy) = y1v;
;         SCAN_INTERLEAVE(13, 4);
;       }
;     }
	v_pk_fma_f32 v[136:137], v[128:129], v[110:111], v[132:133] op_sel_hi:[1,0,1]
	s_waitcnt lgkmcnt(8)
	v_pk_fma_f32 v[112:113], v[92:93], v[128:129], v[112:113] op_sel_hi:[1,0,1]
	v_pk_fma_f32 v[136:137], v[108:109], v[110:111], v[136:137] op_sel:[0,1,0]
	v_pk_fma_f32 v[120:121], v[92:93], v[128:129], v[120:121] op_sel:[0,1,0]
	ds_read_b64 v[108:109], v139 offset:24320
	ds_read_b64 v[110:111], v140 offset:49392
	s_waitcnt lgkmcnt(8)
	v_pk_fma_f32 v[8:9], v[8:9], v[84:85], v[112:113]
	ds_write_b64 v141, v[136:137] offset:3584
	v_pk_fma_f32 v[16:17], v[16:17], v[84:85], v[120:121]
	v_pk_fma_f32 v[114:115], v[94:95], v[128:129], v[114:115] op_sel_hi:[1,0,1]
	v_pk_fma_f32 v[122:123], v[94:95], v[128:129], v[122:123] op_sel:[0,1,0]
	v_pk_fma_f32 v[10:11], v[10:11], v[86:87], v[114:115]
	v_pk_fma_f32 v[18:19], v[18:19], v[86:87], v[122:123]
	v_pk_fma_f32 v[116:117], v[96:97], v[128:129], v[116:117] op_sel_hi:[1,0,1]
	v_pk_fma_f32 v[124:125], v[96:97], v[128:129], v[124:125] op_sel:[0,1,0]
	v_pk_fma_f32 v[4:5], v[4:5], v[88:89], v[116:117]
	v_pk_fma_f32 v[12:13], v[12:13], v[88:89], v[124:125]
	v_pk_fma_f32 v[118:119], v[98:99], v[128:129], v[118:119] op_sel_hi:[1,0,1]
	v_pk_fma_f32 v[126:127], v[98:99], v[128:129], v[126:127] op_sel:[0,1,0]
	v_pk_fma_f32 v[6:7], v[6:7], v[90:91], v[118:119]
	v_pk_fma_f32 v[14:15], v[14:15], v[90:91], v[126:127]
	ds_read_b128 v[92:95], v138 offset:23808
	ds_read_b128 v[96:99], v138 offset:23824
	ds_read_b128 v[84:87], v138 offset:23296
	ds_read_b128 v[88:91], v138 offset:23312
	s_waitcnt lgkmcnt(9)
	v_pk_mul_f32 v[128:129], v[8:9], v[68:69]
	v_pk_mul_f32 v[132:133], v[8:9], v[76:77]
	v_pk_mul_f32 v[130:131], v[16:17], v[68:69]
	v_pk_mul_f32 v[134:135], v[16:17], v[76:77]
	v_pk_fma_f32 v[128:129], v[10:11], v[70:71], v[128:129]
	v_pk_fma_f32 v[132:133], v[10:11], v[78:79], v[132:133]
	v_pk_fma_f32 v[130:131], v[18:19], v[70:71], v[130:131]
	v_pk_fma_f32 v[134:135], v[18:19], v[78:79], v[134:135]
	v_pk_fma_f32 v[128:129], v[4:5], v[72:73], v[128:129]
	v_pk_fma_f32 v[132:133], v[4:5], v[80:81], v[132:133]
	v_pk_fma_f32 v[130:131], v[12:13], v[72:73], v[130:131]
	v_pk_fma_f32 v[134:135], v[12:13], v[80:81], v[134:135]
	v_pk_fma_f32 v[128:129], v[6:7], v[74:75], v[128:129]
	v_pk_fma_f32 v[132:133], v[6:7], v[82:83], v[132:133]
	v_pk_fma_f32 v[130:131], v[14:15], v[74:75], v[130:131]
	v_pk_fma_f32 v[134:135], v[14:15], v[82:83], v[134:135]
	s_waitcnt lgkmcnt(6)
	v_pk_mul_f32 v[112:113], v[108:109], v[100:101] op_sel_hi:[0,1]
	v_pk_mul_f32 v[120:121], v[108:109], v[100:101] op_sel:[1,0]
	v_add_f32_e32 v128, v128, v129
	v_add_f32_e32 v132, v132, v133
	v_add_f32_e32 v129, v130, v131
	v_add_f32_e32 v133, v134, v135
	v_pk_mul_f32 v[114:115], v[108:109], v[102:103] op_sel_hi:[0,1]
	v_pk_mul_f32 v[122:123], v[108:109], v[102:103] op_sel:[1,0]
	v_add_f32_dpp v128, v128, v128 quad_perm:[1,0,3,2] row_mask:0xf bank_mask:0xf bound_ctrl:1
	v_add_f32_dpp v132, v132, v132 quad_perm:[1,0,3,2] row_mask:0xf bank_mask:0xf bound_ctrl:1
	v_add_f32_dpp v129, v129, v129 quad_perm:[1,0,3,2] row_mask:0xf bank_mask:0xf bound_ctrl:1
	v_add_f32_dpp v133, v133, v133 quad_perm:[1,0,3,2] row_mask:0xf bank_mask:0xf bound_ctrl:1
	v_pk_mul_f32 v[116:117], v[108:109], v[104:105] op_sel_hi:[0,1]
	v_pk_mul_f32 v[124:125], v[108:109], v[104:105] op_sel:[1,0]
	v_add_f32_dpp v128, v128, v128 quad_perm:[2,3,0,1] row_mask:0xf bank_mask:0xf bound_ctrl:1
	v_add_f32_dpp v132, v132, v132 quad_perm:[2,3,0,1] row_mask:0xf bank_mask:0xf bound_ctrl:1
	v_add_f32_dpp v129, v129, v129 quad_perm:[2,3,0,1] row_mask:0xf bank_mask:0xf bound_ctrl:1
	v_add_f32_dpp v133, v133, v133 quad_perm:[2,3,0,1] row_mask:0xf bank_mask:0xf bound_ctrl:1
	v_pk_mul_f32 v[118:119], v[108:109], v[106:107] op_sel_hi:[0,1]
	v_pk_mul_f32 v[126:127], v[108:109], v[106:107] op_sel:[1,0]
	v_add_f32_dpp v128, v128, v128 row_half_mirror row_mask:0xf bank_mask:0xf bound_ctrl:1
	v_add_f32_dpp v132, v132, v132 row_half_mirror row_mask:0xf bank_mask:0xf bound_ctrl:1
	v_add_f32_dpp v129, v129, v129 row_half_mirror row_mask:0xf bank_mask:0xf bound_ctrl:1
	v_add_f32_dpp v133, v133, v133 row_half_mirror row_mask:0xf bank_mask:0xf bound_ctrl:1
	s_waitcnt lgkmcnt(5)
	v_pk_fma_f32 v[136:137], v[128:129], v[110:111], v[132:133] op_sel_hi:[1,0,1]
	s_waitcnt lgkmcnt(2)
	v_pk_fma_f32 v[112:113], v[92:93], v[128:129], v[112:113] op_sel_hi:[1,0,1]
	v_pk_fma_f32 v[136:137], v[108:109], v[110:111], v[136:137] op_sel:[0,1,0]
	v_pk_fma_f32 v[120:121], v[92:93], v[128:129], v[120:121] op_sel:[0,1,0]
	s_waitcnt lgkmcnt(0)
	v_pk_fma_f32 v[8:9], v[8:9], v[84:85], v[112:113]
	ds_write_b64 v141, v[136:137] offset:3840
	v_pk_fma_f32 v[16:17], v[16:17], v[84:85], v[120:121]
	v_pk_fma_f32 v[114:115], v[94:95], v[128:129], v[114:115] op_sel_hi:[1,0,1]
	v_pk_fma_f32 v[122:123], v[94:95], v[128:129], v[122:123] op_sel:[0,1,0]
	v_pk_fma_f32 v[10:11], v[10:11], v[86:87], v[114:115]
	v_pk_fma_f32 v[18:19], v[18:19], v[86:87], v[122:123]
	v_pk_fma_f32 v[116:117], v[96:97], v[128:129], v[116:117] op_sel_hi:[1,0,1]
	v_pk_fma_f32 v[124:125], v[96:97], v[128:129], v[124:125] op_sel:[0,1,0]
	v_pk_fma_f32 v[4:5], v[4:5], v[88:89], v[116:117]
	v_pk_fma_f32 v[12:13], v[12:13], v[88:89], v[124:125]
	v_pk_fma_f32 v[118:119], v[98:99], v[128:129], v[118:119] op_sel_hi:[1,0,1]
	v_pk_fma_f32 v[126:127], v[98:99], v[128:129], v[126:127] op_sel:[0,1,0]
	v_pk_fma_f32 v[6:7], v[6:7], v[90:91], v[118:119]
	v_pk_fma_f32 v[14:15], v[14:15], v[90:91], v[126:127]
	s_cmp_eq_u32 s39, 0
	s_cbranch_scc1 .LBB0_283
	s_branch .LBB0_301
